# mout sample task epilogue: 12 output-gate loads issued up front with the first 4 (was 12 serial load-wait-store steps)
# baseline (speedup 1.0000x reference)
; #define MFMA32(a, b, c) __builtin_amdgcn_mfma_f32_32x32x16_bf16((a), (b), (c), 0, 0, 0)
; __device__ __forceinline__ s16x8 pack8(const float (&x)[8]) { u32x4 p; p.x = pk2(x[0], x[1]); p.y = pk2(x[2], x[3]); p.z = pk2(x[4], x[5]); p.w = pk2(x[6], x[7]); return __builtin_bit_cast(s16x8, p); }
; template <bool SAMPLE>
; __device__ __forceinline__ void mout_task(Ctx& C, int l, int unit, int h, int tb, const LAS float* cwl, const LAS float* gainl, LAS float* gsbuf, LAS s16x8* qfl, const bool st) {
;     ...
;         const float* cp = C.in[5] + ((size_t)l * NSLOT_S + unit * 4 + h) * 16384 + r;
; #pragma unroll 1
;         for (int ks = 0; ks < 8; ++ks) { const s16x8 qv = qfl[ks * 64 + lane];
; #pragma unroll
;             for (int vb = 0; vb < 4; ++vb) { float x[8];
; #pragma unroll
;                 for (int e = 0; e < 8; ++e) x[e] = cp[(size_t)(16 * ks + 8 * hi + e) * 128 + 32 * vb];
;                 acc[vb] = MFMA32(pack8(x), qv, acc[vb]); } }
.LBB0_920:
	global_load_dword v132, v[36:37], off offset:-2048
	global_load_dword v133, v[36:37], off offset:-1536
	global_load_dword v134, v[36:37], off offset:-1024
	global_load_dword v135, v[36:37], off offset:-512
	global_load_dword v136, v[36:37], off
	global_load_dword v137, v[36:37], off offset:512
	global_load_dword v138, v[36:37], off offset:1024
	global_load_dword v139, v[36:37], off offset:1536
	global_load_dword v140, v[36:37], off offset:-1920
	global_load_dword v141, v[36:37], off offset:-1408
	global_load_dword v142, v[36:37], off offset:-896
	global_load_dword v143, v[36:37], off offset:-384
	global_load_dword v144, v[36:37], off offset:128
	global_load_dword v145, v[36:37], off offset:640
	global_load_dword v146, v[36:37], off offset:1152
	global_load_dword v147, v[36:37], off offset:1664
	global_load_dword v148, v[36:37], off offset:-1792
	global_load_dword v149, v[36:37], off offset:-1280
	global_load_dword v150, v[36:37], off offset:-768
	global_load_dword v151, v[36:37], off offset:-256
	global_load_dword v152, v[36:37], off offset:256
	global_load_dword v153, v[36:37], off offset:768
	global_load_dword v154, v[36:37], off offset:1280
	global_load_dword v155, v[36:37], off offset:1792
	global_load_dword v156, v[36:37], off offset:-1664
	global_load_dword v157, v[36:37], off offset:-1152
	global_load_dword v158, v[36:37], off offset:-640
	global_load_dword v159, v[36:37], off offset:-128
	global_load_dword v160, v[36:37], off offset:384
	global_load_dword v161, v[36:37], off offset:896
	global_load_dword v162, v[36:37], off offset:1408
	global_load_dword v163, v[36:37], off offset:1920
	v_lshl_add_u64 v[36:37], v[36:37], 0, s[28:29]
	global_load_dword v164, v[36:37], off offset:-2048
	global_load_dword v165, v[36:37], off offset:-1536
	global_load_dword v166, v[36:37], off offset:-1024
	global_load_dword v167, v[36:37], off offset:-512
	global_load_dword v168, v[36:37], off
	global_load_dword v169, v[36:37], off offset:512
	global_load_dword v170, v[36:37], off offset:1024
	global_load_dword v171, v[36:37], off offset:1536
	global_load_dword v172, v[36:37], off offset:-1920
	global_load_dword v173, v[36:37], off offset:-1408
	global_load_dword v174, v[36:37], off offset:-896
	global_load_dword v175, v[36:37], off offset:-384
	global_load_dword v176, v[36:37], off offset:128
	global_load_dword v177, v[36:37], off offset:640
	global_load_dword v178, v[36:37], off offset:1152
	global_load_dword v179, v[36:37], off offset:1664
	global_load_dword v180, v[36:37], off offset:-1792
	global_load_dword v181, v[36:37], off offset:-1280
	global_load_dword v182, v[36:37], off offset:-768
	global_load_dword v183, v[36:37], off offset:-256
	global_load_dword v184, v[36:37], off offset:256
	global_load_dword v47, v[36:37], off offset:768
	global_load_dword v48, v[36:37], off offset:1280
	global_load_dword v49, v[36:37], off offset:1792
	global_load_dword v50, v[36:37], off offset:-1664
	global_load_dword v51, v[36:37], off offset:-1152
	global_load_dword v52, v[36:37], off offset:-640
	global_load_dword v53, v[36:37], off offset:-128
	global_load_dword v54, v[36:37], off offset:384
	global_load_dword v55, v[36:37], off offset:896
	global_load_dword v56, v[36:37], off offset:1408
	global_load_dword v57, v[36:37], off offset:1920
	v_lshl_add_u64 v[36:37], v[36:37], 0, s[28:29]
	ds_read_b128 v[32:35], v131
	ds_read_b128 v[104:107], v131 offset:1024
	s_waitcnt vmcnt(56) lgkmcnt(1)
	v_cvt_pk_bf16_f32 v40, v132, v133
	v_cvt_pk_bf16_f32 v41, v134, v135
	v_cvt_pk_bf16_f32 v42, v136, v137
	v_cvt_pk_bf16_f32 v43, v138, v139
	global_load_dword v132, v[36:37], off offset:-2048
	global_load_dword v133, v[36:37], off offset:-1536
	global_load_dword v134, v[36:37], off offset:-1024
	global_load_dword v135, v[36:37], off offset:-512
	global_load_dword v136, v[36:37], off
	global_load_dword v137, v[36:37], off offset:512
	global_load_dword v138, v[36:37], off offset:1024
	global_load_dword v139, v[36:37], off offset:1536
	v_mfma_f32_32x32x16_bf16 v[0:15], v[40:43], v[32:35], v[0:15]
	s_waitcnt vmcnt(56)
	v_cvt_pk_bf16_f32 v60, v140, v141
	v_cvt_pk_bf16_f32 v61, v142, v143
	v_cvt_pk_bf16_f32 v62, v144, v145
	v_cvt_pk_bf16_f32 v63, v146, v147
	global_load_dword v140, v[36:37], off offset:-1920
	global_load_dword v141, v[36:37], off offset:-1408
	global_load_dword v142, v[36:37], off offset:-896
	global_load_dword v143, v[36:37], off offset:-384
	global_load_dword v144, v[36:37], off offset:128
	global_load_dword v145, v[36:37], off offset:640
	global_load_dword v146, v[36:37], off offset:1152
	global_load_dword v147, v[36:37], off offset:1664
	v_mfma_f32_32x32x16_bf16 v[16:31], v[60:63], v[32:35], v[16:31]
	s_waitcnt vmcnt(56)
	v_cvt_pk_bf16_f32 v40, v148, v149
	v_cvt_pk_bf16_f32 v41, v150, v151
	v_cvt_pk_bf16_f32 v42, v152, v153
	v_cvt_pk_bf16_f32 v43, v154, v155
	global_load_dword v148, v[36:37], off offset:-1792
	global_load_dword v149, v[36:37], off offset:-1280
	global_load_dword v150, v[36:37], off offset:-768
	global_load_dword v151, v[36:37], off offset:-256
	global_load_dword v152, v[36:37], off offset:256
	global_load_dword v153, v[36:37], off offset:768
	global_load_dword v154, v[36:37], off offset:1280
	global_load_dword v155, v[36:37], off offset:1792
	v_mfma_f32_32x32x16_bf16 v[64:79], v[40:43], v[32:35], v[64:79]
	s_waitcnt vmcnt(56)
; #define MFMA32(a, b, c) __builtin_amdgcn_mfma_f32_32x32x16_bf16((a), (b), (c), 0, 0, 0)
; __device__ __forceinline__ s16x8 pack8(const float (&x)[8]) { u32x4 p; p.x = pk2(x[0], x[1]); p.y = pk2(x[2], x[3]); p.z = pk2(x[4], x[5]); p.w = pk2(x[6], x[7]); return __builtin_bit_cast(s16x8, p); }
; template <bool SAMPLE>
; __device__ __forceinline__ void mout_task(Ctx& C, int l, int unit, int h, int tb, const LAS float* cwl, const LAS float* gainl, LAS float* gsbuf, LAS s16x8* qfl, const bool st) {
;     ...
;         const float* cp = C.in[5] + ((size_t)l * NSLOT_S + unit * 4 + h) * 16384 + r;
; #pragma unroll 1
;         for (int ks = 0; ks < 8; ++ks) { const s16x8 qv = qfl[ks * 64 + lane];
; #pragma unroll
;             for (int vb = 0; vb < 4; ++vb) { float x[8];
; #pragma unroll
;                 for (int e = 0; e < 8; ++e) x[e] = cp[(size_t)(16 * ks + 8 * hi + e) * 128 + 32 * vb];
;                 acc[vb] = MFMA32(pack8(x), qv, acc[vb]); } }
	v_cvt_pk_bf16_f32 v60, v156, v157
	v_cvt_pk_bf16_f32 v61, v158, v159
	v_cvt_pk_bf16_f32 v62, v160, v161
	v_cvt_pk_bf16_f32 v63, v162, v163
	global_load_dword v156, v[36:37], off offset:-1664
	global_load_dword v157, v[36:37], off offset:-1152
	global_load_dword v158, v[36:37], off offset:-640
	global_load_dword v159, v[36:37], off offset:-128
	global_load_dword v160, v[36:37], off offset:384
	global_load_dword v161, v[36:37], off offset:896
	global_load_dword v162, v[36:37], off offset:1408
	global_load_dword v163, v[36:37], off offset:1920
	v_mfma_f32_32x32x16_bf16 v[80:95], v[60:63], v[32:35], v[80:95]
	v_lshl_add_u64 v[36:37], v[36:37], 0, s[28:29]
	ds_read_b128 v[32:35], v131 offset:2048
	s_waitcnt vmcnt(56) lgkmcnt(1)
	v_cvt_pk_bf16_f32 v40, v164, v165
	v_cvt_pk_bf16_f32 v41, v166, v167
	v_cvt_pk_bf16_f32 v42, v168, v169
	v_cvt_pk_bf16_f32 v43, v170, v171
	global_load_dword v164, v[36:37], off offset:-2048
	global_load_dword v165, v[36:37], off offset:-1536
	global_load_dword v166, v[36:37], off offset:-1024
	global_load_dword v167, v[36:37], off offset:-512
	global_load_dword v168, v[36:37], off
	global_load_dword v169, v[36:37], off offset:512
	global_load_dword v170, v[36:37], off offset:1024
	global_load_dword v171, v[36:37], off offset:1536
	v_mfma_f32_32x32x16_bf16 v[0:15], v[40:43], v[104:107], v[0:15]
	s_waitcnt vmcnt(56)
	v_cvt_pk_bf16_f32 v60, v172, v173
	v_cvt_pk_bf16_f32 v61, v174, v175
	v_cvt_pk_bf16_f32 v62, v176, v177
	v_cvt_pk_bf16_f32 v63, v178, v179
	global_load_dword v172, v[36:37], off offset:-1920
	global_load_dword v173, v[36:37], off offset:-1408
	global_load_dword v174, v[36:37], off offset:-896
	global_load_dword v175, v[36:37], off offset:-384
	global_load_dword v176, v[36:37], off offset:128
	global_load_dword v177, v[36:37], off offset:640
	global_load_dword v178, v[36:37], off offset:1152
	global_load_dword v179, v[36:37], off offset:1664
	v_mfma_f32_32x32x16_bf16 v[16:31], v[60:63], v[104:107], v[16:31]
	s_waitcnt vmcnt(56)
	v_cvt_pk_bf16_f32 v40, v180, v181
	v_cvt_pk_bf16_f32 v41, v182, v183
	v_cvt_pk_bf16_f32 v42, v184, v47
	v_cvt_pk_bf16_f32 v43, v48, v49
	global_load_dword v180, v[36:37], off offset:-1792
	global_load_dword v181, v[36:37], off offset:-1280
	global_load_dword v182, v[36:37], off offset:-768
	global_load_dword v183, v[36:37], off offset:-256
	global_load_dword v184, v[36:37], off offset:256
	global_load_dword v47, v[36:37], off offset:768
	global_load_dword v48, v[36:37], off offset:1280
	global_load_dword v49, v[36:37], off offset:1792
	v_mfma_f32_32x32x16_bf16 v[64:79], v[40:43], v[104:107], v[64:79]
	s_waitcnt vmcnt(56)
	v_cvt_pk_bf16_f32 v60, v50, v51
	v_cvt_pk_bf16_f32 v61, v52, v53
	v_cvt_pk_bf16_f32 v62, v54, v55
	v_cvt_pk_bf16_f32 v63, v56, v57
	global_load_dword v50, v[36:37], off offset:-1664
	global_load_dword v51, v[36:37], off offset:-1152
	global_load_dword v52, v[36:37], off offset:-640
	global_load_dword v53, v[36:37], off offset:-128
	global_load_dword v54, v[36:37], off offset:384
	global_load_dword v55, v[36:37], off offset:896
	global_load_dword v56, v[36:37], off offset:1408
	global_load_dword v57, v[36:37], off offset:1920
	v_mfma_f32_32x32x16_bf16 v[80:95], v[60:63], v[104:107], v[80:95]
	v_lshl_add_u64 v[36:37], v[36:37], 0, s[28:29]
	ds_read_b128 v[104:107], v131 offset:3072
	s_waitcnt vmcnt(56) lgkmcnt(1)
	v_cvt_pk_bf16_f32 v40, v132, v133
	v_cvt_pk_bf16_f32 v41, v134, v135
	v_cvt_pk_bf16_f32 v42, v136, v137
	v_cvt_pk_bf16_f32 v43, v138, v139
	global_load_dword v132, v[36:37], off offset:-2048
	global_load_dword v133, v[36:37], off offset:-1536
	global_load_dword v134, v[36:37], off offset:-1024
	global_load_dword v135, v[36:37], off offset:-512
	global_load_dword v136, v[36:37], off
	global_load_dword v137, v[36:37], off offset:512
	global_load_dword v138, v[36:37], off offset:1024
	global_load_dword v139, v[36:37], off offset:1536
	v_mfma_f32_32x32x16_bf16 v[0:15], v[40:43], v[32:35], v[0:15]
	s_waitcnt vmcnt(56)
	v_cvt_pk_bf16_f32 v60, v140, v141
	v_cvt_pk_bf16_f32 v61, v142, v143
	v_cvt_pk_bf16_f32 v62, v144, v145
	v_cvt_pk_bf16_f32 v63, v146, v147
	global_load_dword v140, v[36:37], off offset:-1920
	global_load_dword v141, v[36:37], off offset:-1408
	global_load_dword v142, v[36:37], off offset:-896
	global_load_dword v143, v[36:37], off offset:-384
	global_load_dword v144, v[36:37], off offset:128
	global_load_dword v145, v[36:37], off offset:640
	global_load_dword v146, v[36:37], off offset:1152
	global_load_dword v147, v[36:37], off offset:1664
	v_mfma_f32_32x32x16_bf16 v[16:31], v[60:63], v[32:35], v[16:31]
	s_waitcnt vmcnt(56)
	v_cvt_pk_bf16_f32 v40, v148, v149
	v_cvt_pk_bf16_f32 v41, v150, v151
	v_cvt_pk_bf16_f32 v42, v152, v153
	v_cvt_pk_bf16_f32 v43, v154, v155
	global_load_dword v148, v[36:37], off offset:-1792
	global_load_dword v149, v[36:37], off offset:-1280
	global_load_dword v150, v[36:37], off offset:-768
	global_load_dword v151, v[36:37], off offset:-256
	global_load_dword v152, v[36:37], off offset:256
	global_load_dword v153, v[36:37], off offset:768
	global_load_dword v154, v[36:37], off offset:1280
	global_load_dword v155, v[36:37], off offset:1792
	v_mfma_f32_32x32x16_bf16 v[64:79], v[40:43], v[32:35], v[64:79]
	s_waitcnt vmcnt(56)
	v_cvt_pk_bf16_f32 v60, v156, v157
	v_cvt_pk_bf16_f32 v61, v158, v159
	v_cvt_pk_bf16_f32 v62, v160, v161
	v_cvt_pk_bf16_f32 v63, v162, v163
	global_load_dword v156, v[36:37], off offset:-1664
	global_load_dword v157, v[36:37], off offset:-1152
	global_load_dword v158, v[36:37], off offset:-640
	global_load_dword v159, v[36:37], off offset:-128
	global_load_dword v160, v[36:37], off offset:384
	global_load_dword v161, v[36:37], off offset:896
	global_load_dword v162, v[36:37], off offset:1408
	global_load_dword v163, v[36:37], off offset:1920
	v_mfma_f32_32x32x16_bf16 v[80:95], v[60:63], v[32:35], v[80:95]
	v_lshl_add_u64 v[36:37], v[36:37], 0, s[28:29]
	ds_read_b128 v[32:35], v131 offset:4096
	s_waitcnt vmcnt(56) lgkmcnt(1)
; #define MFMA32(a, b, c) __builtin_amdgcn_mfma_f32_32x32x16_bf16((a), (b), (c), 0, 0, 0)
; __device__ __forceinline__ s16x8 pack8(const float (&x)[8]) { u32x4 p; p.x = pk2(x[0], x[1]); p.y = pk2(x[2], x[3]); p.z = pk2(x[4], x[5]); p.w = pk2(x[6], x[7]); return __builtin_bit_cast(s16x8, p); }
; template <bool SAMPLE>
; __device__ __forceinline__ void mout_task(Ctx& C, int l, int unit, int h, int tb, const LAS float* cwl, const LAS float* gainl, LAS float* gsbuf, LAS s16x8* qfl, const bool st) {
;     ...
;         const float* cp = C.in[5] + ((size_t)l * NSLOT_S + unit * 4 + h) * 16384 + r;
; #pragma unroll 1
;         for (int ks = 0; ks < 8; ++ks) { const s16x8 qv = qfl[ks * 64 + lane];
; #pragma unroll
;             for (int vb = 0; vb < 4; ++vb) { float x[8];
; #pragma unroll
;                 for (int e = 0; e < 8; ++e) x[e] = cp[(size_t)(16 * ks + 8 * hi + e) * 128 + 32 * vb];
;                 acc[vb] = MFMA32(pack8(x), qv, acc[vb]); } }
	v_cvt_pk_bf16_f32 v40, v164, v165
	v_cvt_pk_bf16_f32 v41, v166, v167
	v_cvt_pk_bf16_f32 v42, v168, v169
	v_cvt_pk_bf16_f32 v43, v170, v171
	global_load_dword v164, v[36:37], off offset:-2048
	global_load_dword v165, v[36:37], off offset:-1536
	global_load_dword v166, v[36:37], off offset:-1024
	global_load_dword v167, v[36:37], off offset:-512
	global_load_dword v168, v[36:37], off
	global_load_dword v169, v[36:37], off offset:512
	global_load_dword v170, v[36:37], off offset:1024
	global_load_dword v171, v[36:37], off offset:1536
	v_mfma_f32_32x32x16_bf16 v[0:15], v[40:43], v[104:107], v[0:15]
	s_waitcnt vmcnt(56)
	v_cvt_pk_bf16_f32 v60, v172, v173
	v_cvt_pk_bf16_f32 v61, v174, v175
	v_cvt_pk_bf16_f32 v62, v176, v177
	v_cvt_pk_bf16_f32 v63, v178, v179
	global_load_dword v172, v[36:37], off offset:-1920
	global_load_dword v173, v[36:37], off offset:-1408
	global_load_dword v174, v[36:37], off offset:-896
	global_load_dword v175, v[36:37], off offset:-384
	global_load_dword v176, v[36:37], off offset:128
	global_load_dword v177, v[36:37], off offset:640
	global_load_dword v178, v[36:37], off offset:1152
	global_load_dword v179, v[36:37], off offset:1664
	v_mfma_f32_32x32x16_bf16 v[16:31], v[60:63], v[104:107], v[16:31]
	s_waitcnt vmcnt(56)
	v_cvt_pk_bf16_f32 v40, v180, v181
	v_cvt_pk_bf16_f32 v41, v182, v183
	v_cvt_pk_bf16_f32 v42, v184, v47
	v_cvt_pk_bf16_f32 v43, v48, v49
	global_load_dword v180, v[36:37], off offset:-1792
	global_load_dword v181, v[36:37], off offset:-1280
	global_load_dword v182, v[36:37], off offset:-768
	global_load_dword v183, v[36:37], off offset:-256
	global_load_dword v184, v[36:37], off offset:256
	global_load_dword v47, v[36:37], off offset:768
	global_load_dword v48, v[36:37], off offset:1280
	global_load_dword v49, v[36:37], off offset:1792
	v_mfma_f32_32x32x16_bf16 v[64:79], v[40:43], v[104:107], v[64:79]
	s_waitcnt vmcnt(56)
	v_cvt_pk_bf16_f32 v60, v50, v51
	v_cvt_pk_bf16_f32 v61, v52, v53
	v_cvt_pk_bf16_f32 v62, v54, v55
	v_cvt_pk_bf16_f32 v63, v56, v57
	global_load_dword v50, v[36:37], off offset:-1664
	global_load_dword v51, v[36:37], off offset:-1152
	global_load_dword v52, v[36:37], off offset:-640
	global_load_dword v53, v[36:37], off offset:-128
	global_load_dword v54, v[36:37], off offset:384
	global_load_dword v55, v[36:37], off offset:896
	global_load_dword v56, v[36:37], off offset:1408
	global_load_dword v57, v[36:37], off offset:1920
	v_mfma_f32_32x32x16_bf16 v[80:95], v[60:63], v[104:107], v[80:95]
	v_lshl_add_u64 v[36:37], v[36:37], 0, s[28:29]
	ds_read_b128 v[104:107], v131 offset:5120
	s_waitcnt vmcnt(56) lgkmcnt(1)
	v_cvt_pk_bf16_f32 v40, v132, v133
	v_cvt_pk_bf16_f32 v41, v134, v135
	v_cvt_pk_bf16_f32 v42, v136, v137
	v_cvt_pk_bf16_f32 v43, v138, v139
	global_load_dword v132, v[36:37], off offset:-2048
	global_load_dword v133, v[36:37], off offset:-1536
	global_load_dword v134, v[36:37], off offset:-1024
	global_load_dword v135, v[36:37], off offset:-512
	global_load_dword v136, v[36:37], off
	global_load_dword v137, v[36:37], off offset:512
	global_load_dword v138, v[36:37], off offset:1024
	global_load_dword v139, v[36:37], off offset:1536
	v_mfma_f32_32x32x16_bf16 v[0:15], v[40:43], v[32:35], v[0:15]
	s_waitcnt vmcnt(56)
	v_cvt_pk_bf16_f32 v60, v140, v141
	v_cvt_pk_bf16_f32 v61, v142, v143
	v_cvt_pk_bf16_f32 v62, v144, v145
	v_cvt_pk_bf16_f32 v63, v146, v147
	global_load_dword v140, v[36:37], off offset:-1920
	global_load_dword v141, v[36:37], off offset:-1408
	global_load_dword v142, v[36:37], off offset:-896
	global_load_dword v143, v[36:37], off offset:-384
	global_load_dword v144, v[36:37], off offset:128
	global_load_dword v145, v[36:37], off offset:640
	global_load_dword v146, v[36:37], off offset:1152
	global_load_dword v147, v[36:37], off offset:1664
	v_mfma_f32_32x32x16_bf16 v[16:31], v[60:63], v[32:35], v[16:31]
	s_waitcnt vmcnt(56)
	v_cvt_pk_bf16_f32 v40, v148, v149
	v_cvt_pk_bf16_f32 v41, v150, v151
	v_cvt_pk_bf16_f32 v42, v152, v153
	v_cvt_pk_bf16_f32 v43, v154, v155
	global_load_dword v148, v[36:37], off offset:-1792
	global_load_dword v149, v[36:37], off offset:-1280
	global_load_dword v150, v[36:37], off offset:-768
	global_load_dword v151, v[36:37], off offset:-256
	global_load_dword v152, v[36:37], off offset:256
	global_load_dword v153, v[36:37], off offset:768
	global_load_dword v154, v[36:37], off offset:1280
	global_load_dword v155, v[36:37], off offset:1792
	v_mfma_f32_32x32x16_bf16 v[64:79], v[40:43], v[32:35], v[64:79]
	s_waitcnt vmcnt(56)
	v_cvt_pk_bf16_f32 v60, v156, v157
	v_cvt_pk_bf16_f32 v61, v158, v159
	v_cvt_pk_bf16_f32 v62, v160, v161
	v_cvt_pk_bf16_f32 v63, v162, v163
	global_load_dword v156, v[36:37], off offset:-1664
	global_load_dword v157, v[36:37], off offset:-1152
	global_load_dword v158, v[36:37], off offset:-640
	global_load_dword v159, v[36:37], off offset:-128
	global_load_dword v160, v[36:37], off offset:384
	global_load_dword v161, v[36:37], off offset:896
	global_load_dword v162, v[36:37], off offset:1408
	global_load_dword v163, v[36:37], off offset:1920
	v_mfma_f32_32x32x16_bf16 v[80:95], v[60:63], v[32:35], v[80:95]
	v_lshl_add_u64 v[36:37], v[36:37], 0, s[28:29]
	ds_read_b128 v[32:35], v131 offset:6144
	s_waitcnt vmcnt(56) lgkmcnt(1)
	v_cvt_pk_bf16_f32 v40, v164, v165
	v_cvt_pk_bf16_f32 v41, v166, v167
	v_cvt_pk_bf16_f32 v42, v168, v169
	v_cvt_pk_bf16_f32 v43, v170, v171
	global_load_dword v164, v[36:37], off offset:-2048
	global_load_dword v165, v[36:37], off offset:-1536
	global_load_dword v166, v[36:37], off offset:-1024
	global_load_dword v167, v[36:37], off offset:-512
	global_load_dword v168, v[36:37], off
	global_load_dword v169, v[36:37], off offset:512
	global_load_dword v170, v[36:37], off offset:1024
	global_load_dword v171, v[36:37], off offset:1536
	v_mfma_f32_32x32x16_bf16 v[0:15], v[40:43], v[104:107], v[0:15]
	s_waitcnt vmcnt(56)
; #define MFMA32(a, b, c) __builtin_amdgcn_mfma_f32_32x32x16_bf16((a), (b), (c), 0, 0, 0)
; __device__ __forceinline__ s16x8 pack8(const float (&x)[8]) { u32x4 p; p.x = pk2(x[0], x[1]); p.y = pk2(x[2], x[3]); p.z = pk2(x[4], x[5]); p.w = pk2(x[6], x[7]); return __builtin_bit_cast(s16x8, p); }
;     __device__ __forceinline__ bf16* U() const { return (bf16*)(ws + WS_U); }
;     __device__ __forceinline__ bf16* DC() const { return (bf16*)(ws + WS_XN); }
; template <bool SAMPLE>
; __device__ __forceinline__ void mout_task(Ctx& C, int l, int unit, int h, int tb, const LAS float* cwl, const LAS float* gainl, LAS float* gsbuf, LAS s16x8* qfl, const bool st) {
;     ...
;                 for (int e = 0; e < 8; ++e) x[e] = cp[(size_t)(16 * ks + 8 * hi + e) * 128 + 32 * vb];
;                 acc[vb] = MFMA32(pack8(x), qv, acc[vb]); } }
;     } else {
;         const bf16* cp = C.DC() + (size_t)slot * 16384 + (size_t)r * 128 + 8 * hi;
; #pragma unroll 1
;         for (int ks = 0; ks < 8; ++ks) { const s16x8 qv = qfl[ks * 64 + lane];
; #pragma unroll
;             for (int vb = 0; vb < 4; ++vb) acc[vb] = MFMA32(*(const s16x8*)(cp + (size_t)vb * 4096 + 16 * ks), qv, acc[vb]); }
;     }
; #pragma unroll
;     for (int vb = 0; vb < 4; ++vb)
; #pragma unroll
;         for (int i = 0; i < 16; ++i) acc[vb][i] *= winter;
;     float den = 0.f;
;     const int nsb = SAMPLE ? 1 : tb + 1;
; #pragma unroll 1
;     for (int sb = 0; sb < nsb; ++sb) {
;         f32x16 S;
; #pragma unroll
;         for (int i = 0; i < 16; ++i) S[i] = 0.f;
;         const int sl = 32 * sb + r;
;         { s16x8 tk[8];
;           const bf16* kp = C.U() + (grow0 + sl) * UW + C_KM + h * 128 + 8 * hi;
; #pragma unroll
;           for (int ks = 0; ks < 8; ++ks) tk[ks] = *(const s16x8*)(kp + 16 * ks);
	v_cvt_pk_bf16_f32 v60, v172, v173
	v_cvt_pk_bf16_f32 v61, v174, v175
	v_cvt_pk_bf16_f32 v62, v176, v177
	v_cvt_pk_bf16_f32 v63, v178, v179
	global_load_dword v172, v[36:37], off offset:-1920
	global_load_dword v173, v[36:37], off offset:-1408
	global_load_dword v174, v[36:37], off offset:-896
	global_load_dword v175, v[36:37], off offset:-384
	global_load_dword v176, v[36:37], off offset:128
	global_load_dword v177, v[36:37], off offset:640
	global_load_dword v178, v[36:37], off offset:1152
	global_load_dword v179, v[36:37], off offset:1664
	v_mfma_f32_32x32x16_bf16 v[16:31], v[60:63], v[104:107], v[16:31]
	s_waitcnt vmcnt(56)
	v_cvt_pk_bf16_f32 v40, v180, v181
	v_cvt_pk_bf16_f32 v41, v182, v183
	v_cvt_pk_bf16_f32 v42, v184, v47
	v_cvt_pk_bf16_f32 v43, v48, v49
	global_load_dword v180, v[36:37], off offset:-1792
	global_load_dword v181, v[36:37], off offset:-1280
	global_load_dword v182, v[36:37], off offset:-768
	global_load_dword v183, v[36:37], off offset:-256
	global_load_dword v184, v[36:37], off offset:256
	global_load_dword v47, v[36:37], off offset:768
	global_load_dword v48, v[36:37], off offset:1280
	global_load_dword v49, v[36:37], off offset:1792
	v_mfma_f32_32x32x16_bf16 v[64:79], v[40:43], v[104:107], v[64:79]
	s_waitcnt vmcnt(56)
	v_cvt_pk_bf16_f32 v60, v50, v51
	v_cvt_pk_bf16_f32 v61, v52, v53
	v_cvt_pk_bf16_f32 v62, v54, v55
	v_cvt_pk_bf16_f32 v63, v56, v57
	global_load_dword v50, v[36:37], off offset:-1664
	global_load_dword v51, v[36:37], off offset:-1152
	global_load_dword v52, v[36:37], off offset:-640
	global_load_dword v53, v[36:37], off offset:-128
	global_load_dword v54, v[36:37], off offset:384
	global_load_dword v55, v[36:37], off offset:896
	global_load_dword v56, v[36:37], off offset:1408
	global_load_dword v57, v[36:37], off offset:1920
	v_mfma_f32_32x32x16_bf16 v[80:95], v[60:63], v[104:107], v[80:95]
	v_lshl_add_u64 v[36:37], v[36:37], 0, s[28:29]
	ds_read_b128 v[104:107], v131 offset:7168
	s_waitcnt vmcnt(56) lgkmcnt(1)
	v_cvt_pk_bf16_f32 v40, v132, v133
	v_cvt_pk_bf16_f32 v41, v134, v135
	v_cvt_pk_bf16_f32 v42, v136, v137
	v_cvt_pk_bf16_f32 v43, v138, v139
	s_nop 1
	v_mfma_f32_32x32x16_bf16 v[0:15], v[40:43], v[32:35], v[0:15]
	s_waitcnt vmcnt(48)
	v_cvt_pk_bf16_f32 v60, v140, v141
	v_cvt_pk_bf16_f32 v61, v142, v143
	v_cvt_pk_bf16_f32 v62, v144, v145
	v_cvt_pk_bf16_f32 v63, v146, v147
	s_nop 1
	v_mfma_f32_32x32x16_bf16 v[16:31], v[60:63], v[32:35], v[16:31]
	s_waitcnt vmcnt(40)
	v_cvt_pk_bf16_f32 v40, v148, v149
	v_cvt_pk_bf16_f32 v41, v150, v151
	v_cvt_pk_bf16_f32 v42, v152, v153
	v_cvt_pk_bf16_f32 v43, v154, v155
	s_nop 1
	v_mfma_f32_32x32x16_bf16 v[64:79], v[40:43], v[32:35], v[64:79]
	s_waitcnt vmcnt(32)
	v_cvt_pk_bf16_f32 v60, v156, v157
	v_cvt_pk_bf16_f32 v61, v158, v159
	v_cvt_pk_bf16_f32 v62, v160, v161
	v_cvt_pk_bf16_f32 v63, v162, v163
	s_nop 1
	v_mfma_f32_32x32x16_bf16 v[80:95], v[60:63], v[32:35], v[80:95]
	s_waitcnt vmcnt(24) lgkmcnt(0)
	v_cvt_pk_bf16_f32 v40, v164, v165
	v_cvt_pk_bf16_f32 v41, v166, v167
	v_cvt_pk_bf16_f32 v42, v168, v169
	v_cvt_pk_bf16_f32 v43, v170, v171
	s_nop 1
	v_mfma_f32_32x32x16_bf16 v[0:15], v[40:43], v[104:107], v[0:15]
	s_waitcnt vmcnt(16)
	v_cvt_pk_bf16_f32 v60, v172, v173
	v_cvt_pk_bf16_f32 v61, v174, v175
	v_cvt_pk_bf16_f32 v62, v176, v177
	v_cvt_pk_bf16_f32 v63, v178, v179
	s_nop 1
	v_mfma_f32_32x32x16_bf16 v[16:31], v[60:63], v[104:107], v[16:31]
	s_waitcnt vmcnt(8)
	v_cvt_pk_bf16_f32 v40, v180, v181
	v_cvt_pk_bf16_f32 v41, v182, v183
	v_cvt_pk_bf16_f32 v42, v184, v47
	v_cvt_pk_bf16_f32 v43, v48, v49
	s_nop 1
	v_mfma_f32_32x32x16_bf16 v[64:79], v[40:43], v[104:107], v[64:79]
	s_waitcnt vmcnt(0)
	v_cvt_pk_bf16_f32 v60, v50, v51
	v_cvt_pk_bf16_f32 v61, v52, v53
	v_cvt_pk_bf16_f32 v62, v54, v55
	v_cvt_pk_bf16_f32 v63, v56, v57
	s_nop 1
	v_mfma_f32_32x32x16_bf16 v[80:95], v[60:63], v[104:107], v[80:95]
	s_movk_i32 s5, 0x2000
	v_add_f32_e32 v32, v38, v97
	v_sub_f32_e32 v32, v32, v101
	v_mul_f32_e32 v32, 0x3fb8aa3b, v32
	v_exp_f32_e32 v100, v32
	v_lshl_add_u32 v103, v116, 2, s3
	s_mov_b32 s6, 0x3fb8aa3b
	v_cmp_gt_u32_e32 vcc, v192, v129
	v_pk_mul_f32 v[32:33], v[100:101], v[16:17] op_sel_hi:[0,1]
	v_pk_mul_f32 v[16:17], v[100:101], v[64:65] op_sel_hi:[0,1]
	v_or_b32_e32 v64, s4, v192
	v_mul_u32_u24_e32 v64, 0x8400, v64
	v_lshlrev_b32_e32 v64, 1, v64
	v_mov_b32_e32 v65, v193
	v_lshl_add_u64 v[64:65], s[90:91], 0, v[64:65]
	v_pk_mul_f32 v[60:61], v[100:101], v[12:13] op_sel_hi:[0,1]
	v_pk_mul_f32 v[58:59], v[100:101], v[10:11] op_sel_hi:[0,1]
	v_pk_mul_f32 v[56:57], v[100:101], v[8:9] op_sel_hi:[0,1]
	v_pk_mul_f32 v[54:55], v[100:101], v[6:7] op_sel_hi:[0,1]
	v_pk_mul_f32 v[52:53], v[100:101], v[4:5] op_sel_hi:[0,1]
	v_pk_mul_f32 v[50:51], v[100:101], v[2:3] op_sel_hi:[0,1]
	v_pk_mul_f32 v[48:49], v[100:101], v[0:1] op_sel_hi:[0,1]
	v_pk_mul_f32 v[34:35], v[100:101], v[18:19] op_sel_hi:[0,1]
	v_pk_mul_f32 v[18:19], v[100:101], v[66:67] op_sel_hi:[0,1]
	v_pk_mul_f32 v[12:13], v[100:101], v[92:93] op_sel_hi:[0,1]
	v_pk_mul_f32 v[10:11], v[100:101], v[90:91] op_sel_hi:[0,1]
	v_pk_mul_f32 v[8:9], v[100:101], v[88:89] op_sel_hi:[0,1]
	v_pk_mul_f32 v[6:7], v[100:101], v[86:87] op_sel_hi:[0,1]
	v_pk_mul_f32 v[4:5], v[100:101], v[84:85] op_sel_hi:[0,1]
	v_pk_mul_f32 v[2:3], v[100:101], v[82:83] op_sel_hi:[0,1]
	v_pk_mul_f32 v[0:1], v[100:101], v[80:81] op_sel_hi:[0,1]
	v_lshl_add_u64 v[92:93], s[40:41], 1, v[64:65]
	global_load_dwordx4 v[64:67], v[98:99], off offset:3072
	global_load_dwordx4 v[80:83], v[98:99], off offset:3104
	global_load_dwordx4 v[84:87], v[98:99], off offset:3136
	global_load_dwordx4 v[88:91], v[98:99], off offset:3168
	global_load_dwordx4 v[104:107], v[98:99], off offset:3200
; #define LAS __attribute__((address_space(3)))
; __device__ __forceinline__ unsigned pk2(float lo, float hi) { f32x2_t v = {lo, hi}; bf16x2_t b = __builtin_convertvector(v, bf16x2_t); return __builtin_bit_cast(unsigned, b); }
; #define MFMA32(a, b, c) __builtin_amdgcn_mfma_f32_32x32x16_bf16((a), (b), (c), 0, 0, 0)
;     __device__ __forceinline__ bf16* KVt() const { return (bf16*)(ws + WS_KVT); }
; template <bool SAMPLE>
; __device__ __forceinline__ void mout_task(Ctx& C, int l, int unit, int h, int tb, const LAS float* cwl, const LAS float* gainl, LAS float* gsbuf, LAS s16x8* qfl, const bool st) {
;     ...
;           for (int ks = 0; ks < 8; ++ks) tk[ks] = *(const s16x8*)(kp + 16 * ks);
; #pragma unroll
;           for (int ks = 0; ks < 8; ++ks) S = MFMA32(tk[ks], qfl[ks * 64 + lane], S); }
;         const float e0 = (bt - mt) * LOG2E;
; #pragma unroll
;         for (int i4 = 0; i4 < 4; ++i4) { const f32x4 gs = *(const LAS f32x4*)(gsbuf + 32 * sb + 8 * i4 + 4 * hi);
; #pragma unroll
;             for (int e = 0; e < 4; ++e) { const int sidx = 32 * sb + 8 * i4 + 4 * hi + e;
;                 const float wv = (sidx <= tl) ? __builtin_amdgcn_exp2f(e0 + gs[e] * LOG2E) : 0.f;
;                 S[4 * i4 + e] *= wv; den += S[4 * i4 + e]; } }
; #pragma unroll
;         for (int s2 = 0; s2 < 2; ++s2) { u32x4 w; w.x = pk2(S[8 * s2], S[8 * s2 + 1]); w.y = pk2(S[8 * s2 + 2], S[8 * s2 + 3]); w.z = pk2(S[8 * s2 + 4], S[8 * s2 + 5]); w.w = pk2(S[8 * s2 + 6], S[8 * s2 + 7]);
;             const s16x8 pf = __builtin_bit_cast(s16x8, w);
;             const bf16* vp0 = C.KVt() + (size_t)(R_VM + h * 128 + r) * MT + grow0 + 32 * sb + 16 * s2 + 4 * hi;
; #pragma unroll
;             for (int vb = 0; vb < 4; ++vb) { const bf16* vp = vp0 + (size_t)(32 * vb) * MT;
;                 const u32x2 a = *(const u32x2*)vp, bq = *(const u32x2*)(vp + 8); u32x4 vw; vw.x = a.x; vw.y = a.y; vw.z = bq.x; vw.w = bq.y;
	global_load_dwordx4 v[108:111], v[98:99], off offset:3232
	global_load_dwordx4 v[116:119], v[98:99], off offset:3264
	global_load_dwordx4 v[120:123], v[98:99], off offset:3296
	v_pk_mul_f32 v[38:39], v[100:101], v[22:23] op_sel_hi:[0,1]
	v_pk_mul_f32 v[36:37], v[100:101], v[20:21] op_sel_hi:[0,1]
	v_pk_mul_f32 v[22:23], v[100:101], v[70:71] op_sel_hi:[0,1]
	v_pk_mul_f32 v[20:21], v[100:101], v[68:69] op_sel_hi:[0,1]
	ds_read_b128 v[68:71], v127 offset:32768
	ds_read_b128 v[130:133], v127 offset:33792
	v_pk_mul_f32 v[46:47], v[100:101], v[30:31] op_sel_hi:[0,1]
	v_pk_mul_f32 v[44:45], v[100:101], v[28:29] op_sel_hi:[0,1]
	v_pk_mul_f32 v[42:43], v[100:101], v[26:27] op_sel_hi:[0,1]
	v_pk_mul_f32 v[40:41], v[100:101], v[24:25] op_sel_hi:[0,1]
	v_pk_mul_f32 v[30:31], v[100:101], v[78:79] op_sel_hi:[0,1]
	v_pk_mul_f32 v[28:29], v[100:101], v[76:77] op_sel_hi:[0,1]
	v_pk_mul_f32 v[26:27], v[100:101], v[74:75] op_sel_hi:[0,1]
	v_pk_mul_f32 v[24:25], v[100:101], v[72:73] op_sel_hi:[0,1]
	v_pk_mul_f32 v[62:63], v[100:101], v[14:15] op_sel_hi:[0,1]
	v_pk_mul_f32 v[14:15], v[100:101], v[94:95] op_sel_hi:[0,1]
	v_sub_f32_e32 v94, v97, v101
	v_or_b32_e32 v97, 3, v129
	v_or_b32_e32 v113, 17, v129
	v_or_b32_e32 v115, 19, v129
	s_mov_b32 s5, 0x14a00000
	ds_bpermute_b32 v102, v125, v96
	s_lshl_b32 s78, s4, 1
	s_lshl_b32 s4, s4, 2
	s_add_i32 s4, s4, 0
	s_waitcnt vmcnt(7) lgkmcnt(2)
	v_mfma_f32_32x32x16_bf16 v[64:79], v[64:67], v[68:71], 0
	s_waitcnt vmcnt(6) lgkmcnt(1)
	v_mfma_f32_32x32x16_bf16 v[64:79], v[80:83], v[130:133], v[64:79]
	ds_read_b128 v[80:83], v127 offset:34816
	s_waitcnt vmcnt(5) lgkmcnt(0)
	v_mfma_f32_32x32x16_bf16 v[64:79], v[84:87], v[80:83], v[64:79]
	ds_read_b128 v[80:83], v127 offset:35840
	s_waitcnt vmcnt(4) lgkmcnt(0)
	v_mfma_f32_32x32x16_bf16 v[64:79], v[88:91], v[80:83], v[64:79]
	ds_read_b128 v[80:83], v127 offset:36864
	s_waitcnt vmcnt(3) lgkmcnt(0)
	v_mfma_f32_32x32x16_bf16 v[64:79], v[104:107], v[80:83], v[64:79]
	ds_read_b128 v[80:83], v127 offset:37888
	s_waitcnt vmcnt(2) lgkmcnt(0)
	v_mfma_f32_32x32x16_bf16 v[64:79], v[108:111], v[80:83], v[64:79]
	ds_read_b128 v[80:83], v127 offset:38912
	v_or_b32_e32 v108, 9, v129
	v_or_b32_e32 v109, 8, v129
	v_or_b32_e32 v110, 11, v129
	v_or_b32_e32 v111, 10, v129
	s_waitcnt vmcnt(1) lgkmcnt(0)
	v_mfma_f32_32x32x16_bf16 v[64:79], v[116:119], v[80:83], v[64:79]
	ds_read_b128 v[80:83], v127 offset:39936
	v_or_b32_e32 v116, 18, v129
	v_or_b32_e32 v117, 25, v129
	v_or_b32_e32 v118, 24, v129
	v_or_b32_e32 v119, 27, v129
	s_waitcnt vmcnt(0) lgkmcnt(0)
	v_mfma_f32_32x32x16_bf16 v[64:79], v[120:123], v[80:83], v[64:79]
	v_sub_u32_e32 v80, v103, v114
	ds_read_b128 v[104:107], v80 offset:22528
	ds_read_b128 v[88:91], v80 offset:22560
	ds_read_b128 v[84:87], v80 offset:22592
	ds_read_b128 v[80:83], v80 offset:22624
	v_or_b32_e32 v103, 2, v129
	v_or_b32_e32 v114, 16, v129
	v_or_b32_e32 v120, 26, v129
	s_waitcnt lgkmcnt(0)
	v_mov_b32_e32 v95, v83
	v_pk_mul_f32 v[94:95], v[94:95], s[6:7] op_sel_hi:[1,0]
	s_mov_b64 s[6:7], 0x14a00000
	v_fmamk_f32 v98, v105, 0x3fb8aa3b, v94
	v_fmamk_f32 v83, v104, 0x3fb8aa3b, v94
	v_exp_f32_e32 v98, v98
	v_exp_f32_e32 v83, v83
	v_cndmask_b32_e32 v99, 0, v98, vcc
	v_cmp_le_u32_e32 vcc, v129, v192
	s_nop 1
	v_cndmask_b32_e32 v98, 0, v83, vcc
	v_pk_mul_f32 v[64:65], v[64:65], v[98:99]
	v_fmamk_f32 v99, v107, 0x3fb8aa3b, v94
	v_fmamk_f32 v98, v106, 0x3fb8aa3b, v94
	v_exp_f32_e32 v99, v99
	v_exp_f32_e32 v98, v98
	v_cmp_le_u32_e32 vcc, v97, v192
	v_add_f32_e32 v83, 0, v64
	v_add_f32_e32 v83, v65, v83
	v_cndmask_b32_e32 v99, 0, v99, vcc
	v_cmp_le_u32_e32 vcc, v103, v192
	s_nop 1
	v_cndmask_b32_e32 v98, 0, v98, vcc
	v_pk_mul_f32 v[98:99], v[66:67], v[98:99]
	v_fmamk_f32 v67, v89, 0x3fb8aa3b, v94
	v_add_f32_e32 v66, v98, v83
	v_add_f32_e32 v83, v99, v66
	v_fmamk_f32 v66, v88, 0x3fb8aa3b, v94
	v_exp_f32_e32 v67, v67
	v_exp_f32_e32 v66, v66
	v_cmp_le_u32_e32 vcc, v108, v192
	s_nop 1
	v_cndmask_b32_e32 v67, 0, v67, vcc
	v_cmp_le_u32_e32 vcc, v109, v192
	s_nop 1
	v_cndmask_b32_e32 v66, 0, v66, vcc
	v_pk_mul_f32 v[88:89], v[68:69], v[66:67]
	v_fmamk_f32 v67, v91, 0x3fb8aa3b, v94
	v_add_f32_e32 v66, v88, v83
	v_add_f32_e32 v68, v89, v66
	v_fmamk_f32 v66, v90, 0x3fb8aa3b, v94
	v_exp_f32_e32 v67, v67
	v_exp_f32_e32 v66, v66
	v_cmp_le_u32_e32 vcc, v110, v192
	s_nop 1
	v_cndmask_b32_e32 v67, 0, v67, vcc
	v_cmp_le_u32_e32 vcc, v111, v192
	s_nop 1
	v_cndmask_b32_e32 v66, 0, v66, vcc
	v_pk_mul_f32 v[90:91], v[70:71], v[66:67]
	v_fmamk_f32 v67, v85, 0x3fb8aa3b, v94
	v_add_f32_e32 v66, v90, v68
	v_add_f32_e32 v70, v91, v66
	v_fmamk_f32 v66, v84, 0x3fb8aa3b, v94
	v_exp_f32_e32 v67, v67
	v_exp_f32_e32 v66, v66
	v_cmp_le_u32_e32 vcc, v113, v192
	v_add_f32_e32 v71, v94, v95
	v_exp_f32_e32 v71, v71
	v_cndmask_b32_e32 v67, 0, v67, vcc
	v_cmp_le_u32_e32 vcc, v114, v192
	s_nop 1
	v_cndmask_b32_e32 v66, 0, v66, vcc
	v_pk_mul_f32 v[68:69], v[72:73], v[66:67]
	v_fmamk_f32 v67, v87, 0x3fb8aa3b, v94
	v_add_f32_e32 v66, v68, v70
	v_add_f32_e32 v70, v69, v66
	v_fmamk_f32 v66, v86, 0x3fb8aa3b, v94
	v_exp_f32_e32 v67, v67
	v_exp_f32_e32 v66, v66
	v_cmp_le_u32_e32 vcc, v115, v192
	s_nop 1
	v_cndmask_b32_e32 v67, 0, v67, vcc
	v_cmp_le_u32_e32 vcc, v116, v192
	s_nop 1
	v_cndmask_b32_e32 v66, 0, v66, vcc
	v_pk_mul_f32 v[72:73], v[74:75], v[66:67]
	v_fmamk_f32 v67, v81, 0x3fb8aa3b, v94
	v_add_f32_e32 v66, v72, v70
	v_add_f32_e32 v97, v73, v66
	v_fmamk_f32 v66, v80, 0x3fb8aa3b, v94
	v_exp_f32_e32 v67, v67
	v_exp_f32_e32 v66, v66
	v_cmp_le_u32_e32 vcc, v117, v192
	v_fmamk_f32 v70, v82, 0x3fb8aa3b, v94
	v_exp_f32_e32 v70, v70
	v_cndmask_b32_e32 v67, 0, v67, vcc
	v_cmp_le_u32_e32 vcc, v118, v192
	v_cvt_pk_bf16_f32 v74, v64, v65
	v_cvt_pk_bf16_f32 v75, v98, v99
	v_cndmask_b32_e32 v66, 0, v66, vcc
	v_cmp_le_u32_e32 vcc, v119, v192
	v_pk_mul_f32 v[66:67], v[76:77], v[66:67]
	v_cvt_pk_bf16_f32 v76, v88, v89
	v_cndmask_b32_e32 v71, 0, v71, vcc
	v_cmp_le_u32_e32 vcc, v120, v192
	v_lshlrev_b32_e32 v192, 1, v129
	v_lshl_add_u64 v[82:83], v[92:93], 0, v[192:193]
	v_cndmask_b32_e32 v70, 0, v70, vcc
	v_add_co_u32_e32 v64, vcc, s5, v82
	v_pk_mul_f32 v[70:71], v[78:79], v[70:71]
	s_nop 0
	v_addc_co_u32_e32 v65, vcc, 0, v83, vcc
	v_lshl_add_u64 v[84:85], v[82:83], 0, s[6:7]
	global_load_dwordx2 v[78:79], v[64:65], off
	global_load_dwordx2 v[80:81], v[84:85], off offset:16
	s_mov_b32 s5, 0x14c10000
	v_add_co_u32_e32 v64, vcc, s5, v82
	v_cvt_pk_bf16_f32 v77, v90, v91
	s_nop 0
	v_addc_co_u32_e32 v65, vcc, 0, v83, vcc
	s_waitcnt vmcnt(0)
; #define LAS __attribute__((address_space(3)))
; __device__ __forceinline__ unsigned pk2(float lo, float hi) { f32x2_t v = {lo, hi}; bf16x2_t b = __builtin_convertvector(v, bf16x2_t); return __builtin_bit_cast(unsigned, b); }
; __device__ __forceinline__ float fexp(float x) { return __builtin_amdgcn_exp2f(x * LOG2E); }
; #define MFMA32(a, b, c) __builtin_amdgcn_mfma_f32_32x32x16_bf16((a), (b), (c), 0, 0, 0)
;     __device__ __forceinline__ bf16* U() const { return (bf16*)(ws + WS_U); }
;     __device__ __forceinline__ bf16* KVt() const { return (bf16*)(ws + WS_KVT); }
; template <bool SAMPLE>
; __device__ __forceinline__ void mout_task(Ctx& C, int l, int unit, int h, int tb, const LAS float* cwl, const LAS float* gainl, LAS float* gsbuf, LAS s16x8* qfl, const bool st) {
;     ...
; #pragma unroll
;         for (int s2 = 0; s2 < 2; ++s2) { u32x4 w; w.x = pk2(S[8 * s2], S[8 * s2 + 1]); w.y = pk2(S[8 * s2 + 2], S[8 * s2 + 3]); w.z = pk2(S[8 * s2 + 4], S[8 * s2 + 5]); w.w = pk2(S[8 * s2 + 6], S[8 * s2 + 7]);
;             const s16x8 pf = __builtin_bit_cast(s16x8, w);
;             const bf16* vp0 = C.KVt() + (size_t)(R_VM + h * 128 + r) * MT + grow0 + 32 * sb + 16 * s2 + 4 * hi;
; #pragma unroll
;             for (int vb = 0; vb < 4; ++vb) { const bf16* vp = vp0 + (size_t)(32 * vb) * MT;
;                 const u32x2 a = *(const u32x2*)vp, bq = *(const u32x2*)(vp + 8); u32x4 vw; vw.x = a.x; vw.y = a.y; vw.z = bq.x; vw.w = bq.y;
;                 acc[vb] = MFMA32(__builtin_bit_cast(s16x8, vw), pf, acc[vb]); } }
;     }
;     den += __shfl_xor(den, 32);
;     den += winter * qn;
;     const float inv = __builtin_amdgcn_rcpf(fmaxf(fabsf(den), fexp(-mt)));
;     float ss = 0.f;
; #pragma unroll
;     for (int vb = 0; vb < 4; ++vb)
; #pragma unroll
;         for (int i = 0; i < 16; ++i) { acc[vb][i] *= inv; ss += acc[vb][i] * acc[vb][i]; }
;     ss += __shfl_xor(ss, 32);
;     const float rn = rsqrtf(ss * (1.f / 128.f) + EPS);
;     int lane2 = lane; asm volatile("" : "+v"(lane2));
;     const int hi2 = lane2 >> 5;
;     bf16* orow = C.U() + (grow0 + 32 * tb + (lane2 & 31)) * UW + C_OM + h * 128;
; #pragma unroll
;     for (int vb = 0; vb < 4; ++vb)
; #pragma unroll
;         for (int i4 = 0; i4 < 4; ++i4) { const int v0 = 32 * vb + 8 * i4 + 4 * hi2;
;             const u32x2 ow = *(const u32x2*)(orow + v0); const f32x4 gn = *(const LAS f32x4*)(gainl + h * 128 + v0);
	v_mfma_f32_32x32x16_bf16 v[48:63], v[78:81], v[74:77], v[48:63]
	global_load_dwordx2 v[78:79], v[64:65], off
	global_load_dwordx2 v[80:81], v[64:65], off offset:16
	s_mov_b32 s5, 0x14e20000
	v_add_co_u32_e32 v86, vcc, s5, v82
	s_mov_b32 s5, 0x15030000
	s_nop 0
	v_addc_co_u32_e32 v87, vcc, 0, v83, vcc
	s_waitcnt vmcnt(0)
	v_mfma_f32_32x32x16_bf16 v[32:47], v[78:81], v[74:77], v[32:47]
	global_load_dwordx2 v[78:79], v[86:87], off
	global_load_dwordx2 v[80:81], v[86:87], off offset:16
	v_add_co_u32_e32 v82, vcc, s5, v82
	s_nop 1
	v_addc_co_u32_e32 v83, vcc, 0, v83, vcc
	s_waitcnt vmcnt(0)
	v_mfma_f32_32x32x16_bf16 v[16:31], v[78:81], v[74:77], v[16:31]
	global_load_dwordx2 v[78:79], v[82:83], off
	global_load_dwordx2 v[80:81], v[82:83], off offset:16
	s_waitcnt vmcnt(0)
	v_mfma_f32_32x32x16_bf16 v[0:15], v[78:81], v[74:77], v[0:15]
	global_load_dwordx2 v[78:79], v[84:85], off offset:32
	global_load_dwordx2 v[80:81], v[84:85], off offset:48
	v_cvt_pk_bf16_f32 v74, v68, v69
	v_cvt_pk_bf16_f32 v75, v72, v73
	v_cvt_pk_bf16_f32 v76, v66, v67
	v_cvt_pk_bf16_f32 v77, v70, v71
	s_waitcnt vmcnt(0)
	s_nop 0
	v_mfma_f32_32x32x16_bf16 v[48:63], v[78:81], v[74:77], v[48:63]
	global_load_dwordx2 v[78:79], v[64:65], off offset:32
	global_load_dwordx2 v[80:81], v[64:65], off offset:48
	v_add_f32_e32 v64, v66, v97
	v_add_f32_e32 v64, v67, v64
	v_add_f32_e32 v64, v70, v64
	v_add_f32_e32 v97, v71, v64
	ds_bpermute_b32 v103, v125, v97
	s_waitcnt lgkmcnt(0)
	v_pk_add_f32 v[64:65], v[96:97], v[102:103]
	s_waitcnt vmcnt(0)
	v_mfma_f32_32x32x16_bf16 v[32:47], v[78:81], v[74:77], v[32:47]
	global_load_dwordx2 v[78:79], v[86:87], off offset:32
	global_load_dwordx2 v[80:81], v[86:87], off offset:48
	v_fmac_f32_e32 v65, v100, v64
	v_mul_f32_e32 v64, 0xbfb8aa3b, v101
	v_exp_f32_e32 v64, v64
	s_nop 0
	v_max_f32_e64 v64, |v65|, v64
	s_waitcnt vmcnt(0)
	v_mfma_f32_32x32x16_bf16 v[16:31], v[78:81], v[74:77], v[16:31]
	global_load_dwordx2 v[78:79], v[82:83], off offset:32
	global_load_dwordx2 v[80:81], v[82:83], off offset:48
	s_waitcnt vmcnt(0)
	v_mfma_f32_32x32x16_bf16 v[0:15], v[78:81], v[74:77], v[0:15]
	v_rcp_f32_e32 v80, v64
	s_nop 10
	v_pk_mul_f32 v[72:73], v[10:11], v[80:81] op_sel_hi:[1,0]
	v_pk_mul_f32 v[68:69], v[12:13], v[80:81] op_sel_hi:[1,0]
	v_and_or_b32 v12, v112, 31, s40
	v_mov_b64_e32 v[10:11], s[90:91]
	v_mad_u64_u32 v[10:11], s[6:7], v12, s61, v[10:11]
	v_ashrrev_i32_e32 v12, 3, v112
	v_mad_i32_i24 v11, s41, v221, v11
	v_and_b32_e32 v12, -4, v12
	v_lshl_add_u64 v[10:11], v[10:11], 0, s[78:79]
	v_ashrrev_i32_e32 v13, 31, v12
	v_lshl_add_u64 v[10:11], v[12:13], 1, v[10:11]
	s_mov_b64 s[6:7], 0x1000
	v_add_co_u32_e32 v82, vcc, s60, v10
	v_pk_mul_f32 v[14:15], v[14:15], v[80:81] op_sel_hi:[1,0]
	v_lshl_add_u64 v[70:71], v[10:11], 0, s[6:7]
	v_addc_co_u32_e32 v83, vcc, 0, v11, vcc
	v_lshl_add_u32 v81, v12, 2, s4
	global_load_dwordx2 v[86:87], v[82:83], off
	ds_read_b128 v[64:67], v81 offset:20480
	ds_read_b128 v[10:13], v81 offset:20512
	v_pk_mul_f32 v[90:91], v[48:49], v[80:81] op_sel_hi:[1,0]
	global_load_dwordx2 v[48:49], v[70:71], off offset:16
	global_load_dwordx2 v[116:117], v[70:71], off offset:48
	v_pk_mul_f32 v[102:103], v[52:53], v[80:81] op_sel_hi:[1,0]
	global_load_dwordx2 v[52:53], v[70:71], off offset:32
	global_load_dwordx2 v[168:169], v[70:71], off offset:64
	global_load_dwordx2 v[170:171], v[70:71], off offset:80
	global_load_dwordx2 v[172:173], v[70:71], off offset:96
	global_load_dwordx2 v[174:175], v[70:71], off offset:112
	global_load_dwordx2 v[176:177], v[70:71], off offset:128
	global_load_dwordx2 v[180:181], v[70:71], off offset:144
	global_load_dwordx2 v[182:183], v[70:71], off offset:160
	global_load_dwordx2 v[186:187], v[70:71], off offset:176
	global_load_dwordx2 v[194:195], v[70:71], off offset:192
	global_load_dwordx2 v[196:197], v[70:71], off offset:208
	global_load_dwordx2 v[198:199], v[70:71], off offset:224
	global_load_dwordx2 v[214:215], v[70:71], off offset:240
	v_pk_mul_f32 v[88:89], v[50:51], v[80:81] op_sel_hi:[1,0]
	v_pk_mul_f32 v[94:95], v[90:91], v[90:91]
	v_pk_mul_f32 v[92:93], v[88:89], v[88:89]
	v_pk_mul_f32 v[100:101], v[54:55], v[80:81] op_sel_hi:[1,0]
	v_pk_mul_f32 v[58:59], v[58:59], v[80:81] op_sel_hi:[1,0]
	v_pk_mul_f32 v[56:57], v[56:57], v[80:81] op_sel_hi:[1,0]
	v_pk_mul_f32 v[126:127], v[62:63], v[80:81] op_sel_hi:[1,0]
	v_pk_mul_f32 v[130:131], v[60:61], v[80:81] op_sel_hi:[1,0]
	v_pk_mul_f32 v[134:135], v[34:35], v[80:81] op_sel_hi:[1,0]
	v_pk_mul_f32 v[138:139], v[32:33], v[80:81] op_sel_hi:[1,0]
	v_pk_mul_f32 v[60:61], v[42:43], v[80:81] op_sel_hi:[1,0]
	v_pk_mul_f32 v[62:63], v[40:41], v[80:81] op_sel_hi:[1,0]
	v_pk_mul_f32 v[46:47], v[46:47], v[80:81] op_sel_hi:[1,0]
	v_pk_mul_f32 v[44:45], v[44:45], v[80:81] op_sel_hi:[1,0]
	v_pk_mul_f32 v[40:41], v[18:19], v[80:81] op_sel_hi:[1,0]
	v_pk_mul_f32 v[42:43], v[16:17], v[80:81] op_sel_hi:[1,0]
	v_pk_mul_f32 v[32:33], v[26:27], v[80:81] op_sel_hi:[1,0]
	v_pk_mul_f32 v[34:35], v[24:25], v[80:81] op_sel_hi:[1,0]
	v_pk_mul_f32 v[24:25], v[30:31], v[80:81] op_sel_hi:[1,0]
	v_pk_mul_f32 v[26:27], v[28:29], v[80:81] op_sel_hi:[1,0]
	v_pk_mul_f32 v[16:17], v[6:7], v[80:81] op_sel_hi:[1,0]
	v_pk_mul_f32 v[18:19], v[4:5], v[80:81] op_sel_hi:[1,0]
	v_pk_mul_f32 v[6:7], v[8:9], v[80:81] op_sel_hi:[1,0]
	v_pk_mul_f32 v[106:107], v[102:103], v[102:103]
	v_pk_mul_f32 v[104:105], v[100:101], v[100:101]
	v_pk_mul_f32 v[114:115], v[56:57], v[56:57]
	v_pk_mul_f32 v[112:113], v[58:59], v[58:59]
	v_pk_mul_f32 v[132:133], v[130:131], v[130:131]
	v_pk_mul_f32 v[128:129], v[126:127], v[126:127]
	v_pk_mul_f32 v[140:141], v[138:139], v[138:139]
	v_pk_mul_f32 v[136:137], v[134:135], v[134:135]
	v_pk_mul_f32 v[148:149], v[62:63], v[62:63]
	v_pk_mul_f32 v[146:147], v[60:61], v[60:61]
	v_pk_mul_f32 v[152:153], v[44:45], v[44:45]
	v_pk_mul_f32 v[150:151], v[46:47], v[46:47]
	v_pk_mul_f32 v[156:157], v[42:43], v[42:43]
	v_pk_mul_f32 v[154:155], v[40:41], v[40:41]
	v_pk_mul_f32 v[164:165], v[34:35], v[34:35]
	v_pk_mul_f32 v[162:163], v[32:33], v[32:33]
	v_pk_mul_f32 v[28:29], v[26:27], v[26:27]
	v_pk_mul_f32 v[30:31], v[24:25], v[24:25]
	v_pk_mul_f32 v[4:5], v[18:19], v[18:19]
	v_pk_mul_f32 v[166:167], v[16:17], v[16:17]
	v_pk_mul_f32 v[8:9], v[6:7], v[6:7]
	v_pk_mul_f32 v[74:75], v[72:73], v[72:73]
	v_pk_mul_f32 v[76:77], v[68:69], v[68:69]
	v_pk_mul_f32 v[78:79], v[14:15], v[14:15]
	s_waitcnt vmcnt(15)
; #define LAS __attribute__((address_space(3)))
; __device__ __forceinline__ unsigned pk2(float lo, float hi) { f32x2_t v = {lo, hi}; bf16x2_t b = __builtin_convertvector(v, bf16x2_t); return __builtin_bit_cast(unsigned, b); }
; __device__ __forceinline__ float bflo(unsigned w) { return __uint_as_float(w << 16); }
; __device__ __forceinline__ float bfhi(unsigned w) { return __uint_as_float(w & 0xffff0000u); }
; __device__ __forceinline__ float sigmoidf_(float x) { return __builtin_amdgcn_rcpf(1.f + fexp(-x)); }
;     __device__ __forceinline__ bf16* U() const { return (bf16*)(ws + WS_U); }
; template <bool SAMPLE>
; __device__ __forceinline__ void mout_task(Ctx& C, int l, int unit, int h, int tb, const LAS float* cwl, const LAS float* gainl, LAS float* gsbuf, LAS s16x8* qfl, const bool st) {
;     ...
;     float ss = 0.f;
; #pragma unroll
;     for (int vb = 0; vb < 4; ++vb)
; #pragma unroll
;         for (int i = 0; i < 16; ++i) { acc[vb][i] *= inv; ss += acc[vb][i] * acc[vb][i]; }
;     ss += __shfl_xor(ss, 32);
;     const float rn = rsqrtf(ss * (1.f / 128.f) + EPS);
;     int lane2 = lane; asm volatile("" : "+v"(lane2));
;     const int hi2 = lane2 >> 5;
;     bf16* orow = C.U() + (grow0 + 32 * tb + (lane2 & 31)) * UW + C_OM + h * 128;
; #pragma unroll
;     for (int vb = 0; vb < 4; ++vb)
; #pragma unroll
;         for (int i4 = 0; i4 < 4; ++i4) { const int v0 = 32 * vb + 8 * i4 + 4 * hi2;
;             const u32x2 ow = *(const u32x2*)(orow + v0); const f32x4 gn = *(const LAS f32x4*)(gainl + h * 128 + v0);
;             const float y0 = acc[vb][4 * i4] * rn * gn[0] * sigmoidf_(bflo(ow.x)), y1 = acc[vb][4 * i4 + 1] * rn * gn[1] * sigmoidf_(bfhi(ow.x));
;             const float y2 = acc[vb][4 * i4 + 2] * rn * gn[2] * sigmoidf_(bflo(ow.y)), y3 = acc[vb][4 * i4 + 3] * rn * gn[3] * sigmoidf_(bfhi(ow.y));
;             u32x2 w; w.x = pk2(y0, y1); w.y = pk2(y2, y3); if (st) *(u32x2*)(orow + v0) = w; if (i4 == 3) asm volatile("" ::: "memory"); }
	v_lshlrev_b32_e32 v84, 16, v86
	v_and_b32_e32 v85, 0xffff0000, v86
	v_lshlrev_b32_e32 v86, 16, v87
	s_waitcnt vmcnt(14)
	v_lshlrev_b32_e32 v50, 16, v48
	s_waitcnt vmcnt(13)
	v_lshlrev_b32_e32 v118, 16, v116
	v_and_b32_e32 v116, 0xffff0000, v116
	v_mul_f32_e32 v116, 0xbfb8aa3b, v116
	v_exp_f32_e32 v116, v116
	v_mul_f32_e32 v118, 0xbfb8aa3b, v118
	v_exp_f32_e32 v118, v118
	v_and_b32_e32 v48, 0xffff0000, v48
	v_add_f32_e32 v116, 1.0, v116
	v_rcp_f32_e32 v121, v116
	v_lshlrev_b32_e32 v116, 16, v117
	v_mul_f32_e32 v116, 0xbfb8aa3b, v116
	v_exp_f32_e32 v116, v116
	v_add_f32_e32 v118, 1.0, v118
	v_rcp_f32_e32 v120, v118
	v_pk_mul_f32 v[118:119], v[36:37], v[80:81] op_sel_hi:[1,0]
	v_add_f32_e32 v116, 1.0, v116
	v_rcp_f32_e32 v122, v116
	v_and_b32_e32 v116, 0xffff0000, v117
	v_mul_f32_e32 v116, 0xbfb8aa3b, v116
	v_exp_f32_e32 v116, v116
	v_pk_mul_f32 v[36:37], v[22:23], v[80:81] op_sel_hi:[1,0]
	v_pk_mul_f32 v[22:23], v[0:1], v[80:81] op_sel_hi:[1,0]
	v_pk_mul_f32 v[144:145], v[118:119], v[118:119]
	v_add_f32_e32 v116, 1.0, v116
	v_rcp_f32_e32 v123, v116
	v_pk_mul_f32 v[116:117], v[38:39], v[80:81] op_sel_hi:[1,0]
	v_pk_mul_f32 v[38:39], v[20:21], v[80:81] op_sel_hi:[1,0]
	v_pk_mul_f32 v[20:21], v[2:3], v[80:81] op_sel_hi:[1,0]
	v_add_f32_e32 v80, v94, v95
	v_add_f32_e32 v80, v92, v80
	v_add_f32_e32 v80, v93, v80
	v_add_f32_e32 v80, v106, v80
	v_add_f32_e32 v80, v107, v80
	v_add_f32_e32 v80, v104, v80
	v_add_f32_e32 v80, v105, v80
	v_add_f32_e32 v80, v114, v80
	v_add_f32_e32 v80, v115, v80
	v_add_f32_e32 v80, v112, v80
	v_add_f32_e32 v80, v113, v80
	v_add_f32_e32 v80, v132, v80
	v_add_f32_e32 v80, v133, v80
	v_add_f32_e32 v80, v128, v80
	v_add_f32_e32 v80, v129, v80
	v_add_f32_e32 v80, v140, v80
	v_add_f32_e32 v80, v141, v80
	v_add_f32_e32 v80, v136, v80
	v_add_f32_e32 v80, v137, v80
	v_add_f32_e32 v80, v144, v80
	v_pk_mul_f32 v[142:143], v[116:117], v[116:117]
	v_add_f32_e32 v80, v145, v80
	v_add_f32_e32 v80, v142, v80
	v_add_f32_e32 v80, v143, v80
	v_add_f32_e32 v80, v148, v80
	v_add_f32_e32 v80, v149, v80
	v_add_f32_e32 v80, v146, v80
	v_add_f32_e32 v80, v147, v80
	v_add_f32_e32 v80, v152, v80
	v_add_f32_e32 v80, v153, v80
	v_add_f32_e32 v80, v150, v80
	v_add_f32_e32 v80, v151, v80
	v_add_f32_e32 v80, v156, v80
	v_add_f32_e32 v80, v157, v80
	v_add_f32_e32 v80, v154, v80
	v_pk_mul_f32 v[160:161], v[38:39], v[38:39]
	v_add_f32_e32 v80, v155, v80
	v_add_f32_e32 v80, v160, v80
	v_pk_mul_f32 v[158:159], v[36:37], v[36:37]
	v_add_f32_e32 v80, v161, v80
	v_add_f32_e32 v80, v158, v80
	v_add_f32_e32 v80, v159, v80
	v_add_f32_e32 v80, v164, v80
	v_add_f32_e32 v80, v165, v80
	v_add_f32_e32 v80, v162, v80
	v_add_f32_e32 v80, v163, v80
	v_add_f32_e32 v28, v28, v80
	v_add_f32_e32 v28, v29, v28
	v_add_f32_e32 v28, v30, v28
	v_pk_mul_f32 v[0:1], v[22:23], v[22:23]
	v_add_f32_e32 v28, v31, v28
	v_add_f32_e32 v0, v0, v28
	v_pk_mul_f32 v[2:3], v[20:21], v[20:21]
	v_add_f32_e32 v0, v1, v0
	v_add_f32_e32 v0, v2, v0
	v_add_f32_e32 v0, v3, v0
	v_add_f32_e32 v0, v4, v0
	v_add_f32_e32 v0, v5, v0
	v_add_f32_e32 v0, v166, v0
	v_add_f32_e32 v0, v167, v0
	v_add_f32_e32 v0, v8, v0
	v_add_f32_e32 v0, v9, v0
	v_add_f32_e32 v0, v74, v0
	v_add_f32_e32 v0, v75, v0
	v_add_f32_e32 v0, v76, v0
	v_mul_f32_e32 v48, 0xbfb8aa3b, v48
	v_add_f32_e32 v0, v77, v0
	v_exp_f32_e32 v48, v48
	v_add_f32_e32 v0, v78, v0
	v_add_f32_e32 v0, v79, v0
	s_waitcnt vmcnt(12)
	v_lshlrev_b32_e32 v54, 16, v52
	v_and_b32_e32 v52, 0xffff0000, v52
	ds_bpermute_b32 v1, v125, v0
	v_mul_f32_e32 v52, 0xbfb8aa3b, v52
	v_add_f32_e32 v48, 1.0, v48
	v_exp_f32_e32 v52, v52
	v_rcp_f32_e32 v97, v48
	v_lshlrev_b32_e32 v48, 16, v49
	v_mul_f32_e32 v48, 0xbfb8aa3b, v48
	v_exp_f32_e32 v48, v48
	s_waitcnt lgkmcnt(0)
	v_add_f32_e32 v0, v0, v1
	v_mov_b32_e32 v2, 0x358637bd
	v_and_b32_e32 v87, 0xffff0000, v87
	v_add_f32_e32 v52, 1.0, v52
	v_fmamk_f32 v0, v0, 0x3c000000, v2
	v_mul_f32_e32 v84, 0xbfb8aa3b, v84
	v_mul_f32_e32 v85, 0xbfb8aa3b, v85
	v_mul_f32_e32 v86, 0xbfb8aa3b, v86
	v_mul_f32_e32 v87, 0xbfb8aa3b, v87
	v_rcp_f32_e32 v109, v52
	v_lshlrev_b32_e32 v52, 16, v53
	v_cmp_gt_f32_e32 vcc, s65, v0
	v_mul_f32_e32 v1, 0x4b800000, v0
	v_exp_f32_e32 v84, v84
	v_exp_f32_e32 v85, v85
	v_exp_f32_e32 v86, v86
	v_exp_f32_e32 v87, v87
	v_mul_f32_e32 v52, 0xbfb8aa3b, v52
	v_cndmask_b32_e32 v0, v0, v1, vcc
	v_add_f32_e32 v48, 1.0, v48
	v_exp_f32_e32 v52, v52
	v_rsq_f32_e32 v0, v0
	v_rcp_f32_e32 v98, v48
	v_and_b32_e32 v48, 0xffff0000, v49
	v_mul_f32_e32 v50, 0xbfb8aa3b, v50
	v_mul_f32_e32 v48, 0xbfb8aa3b, v48
	v_add_f32_e32 v84, 1.0, v84
	v_add_f32_e32 v85, 1.0, v85
	v_add_f32_e32 v86, 1.0, v86
	v_add_f32_e32 v87, 1.0, v87
	v_exp_f32_e32 v50, v50
	v_exp_f32_e32 v48, v48
	v_rcp_f32_e32 v84, v84
	v_rcp_f32_e32 v85, v85
	v_rcp_f32_e32 v86, v86
	v_rcp_f32_e32 v87, v87
	v_add_f32_e32 v52, 1.0, v52
	v_mul_f32_e32 v1, 0x45800000, v0
	v_rcp_f32_e32 v110, v52
	v_and_b32_e32 v52, 0xffff0000, v53
	v_cndmask_b32_e32 v4, v0, v1, vcc
	v_mul_f32_e32 v54, 0xbfb8aa3b, v54
	v_mul_f32_e32 v52, 0xbfb8aa3b, v52
	v_pk_mul_f32 v[0:1], v[90:91], v[4:5] op_sel_hi:[1,0]
	v_pk_mul_f32 v[2:3], v[88:89], v[4:5] op_sel_hi:[1,0]
	v_add_f32_e32 v50, 1.0, v50
	v_add_f32_e32 v48, 1.0, v48
	v_exp_f32_e32 v54, v54
	v_exp_f32_e32 v52, v52
	v_pk_mul_f32 v[0:1], v[64:65], v[0:1]
	v_pk_mul_f32 v[2:3], v[66:67], v[2:3]
	v_rcp_f32_e32 v96, v50
	v_rcp_f32_e32 v99, v48
	v_pk_mul_f32 v[0:1], v[84:85], v[0:1]
	v_pk_mul_f32 v[2:3], v[86:87], v[2:3]
	v_cvt_pk_bf16_f32 v0, v0, v1
	v_cvt_pk_bf16_f32 v1, v2, v3
	ds_read_b128 v[48:51], v81 offset:20544
	global_store_dwordx2 v[82:83], v[0:1], off
	v_pk_mul_f32 v[0:1], v[102:103], v[4:5] op_sel_hi:[1,0]
	v_pk_mul_f32 v[2:3], v[100:101], v[4:5] op_sel_hi:[1,0]
	v_add_f32_e32 v54, 1.0, v54
	v_add_f32_e32 v52, 1.0, v52
	v_pk_mul_f32 v[0:1], v[10:11], v[0:1]
	v_pk_mul_f32 v[2:3], v[12:13], v[2:3]
	v_rcp_f32_e32 v108, v54
	v_rcp_f32_e32 v111, v52
	v_pk_mul_f32 v[0:1], v[96:97], v[0:1]
	v_pk_mul_f32 v[2:3], v[98:99], v[2:3]
	v_cvt_pk_bf16_f32 v0, v0, v1
	v_cvt_pk_bf16_f32 v1, v2, v3
	ds_read_b128 v[52:55], v81 offset:20576
	global_store_dwordx2 v[70:71], v[0:1], off offset:16
	v_pk_mul_f32 v[0:1], v[56:57], v[4:5] op_sel_hi:[1,0]
	v_pk_mul_f32 v[2:3], v[58:59], v[4:5] op_sel_hi:[1,0]
	s_waitcnt lgkmcnt(1)
; #define LAS __attribute__((address_space(3)))
; __device__ __forceinline__ unsigned pk2(float lo, float hi) { f32x2_t v = {lo, hi}; bf16x2_t b = __builtin_convertvector(v, bf16x2_t); return __builtin_bit_cast(unsigned, b); }
; __device__ __forceinline__ float bflo(unsigned w) { return __uint_as_float(w << 16); }
; __device__ __forceinline__ float bfhi(unsigned w) { return __uint_as_float(w & 0xffff0000u); }
; __device__ __forceinline__ float sigmoidf_(float x) { return __builtin_amdgcn_rcpf(1.f + fexp(-x)); }
; template <bool SAMPLE>
; __device__ __forceinline__ void mout_task(Ctx& C, int l, int unit, int h, int tb, const LAS float* cwl, const LAS float* gainl, LAS float* gsbuf, LAS s16x8* qfl, const bool st) {
;     ...
;         for (int i4 = 0; i4 < 4; ++i4) { const int v0 = 32 * vb + 8 * i4 + 4 * hi2;
;             const u32x2 ow = *(const u32x2*)(orow + v0); const f32x4 gn = *(const LAS f32x4*)(gainl + h * 128 + v0);
;             const float y0 = acc[vb][4 * i4] * rn * gn[0] * sigmoidf_(bflo(ow.x)), y1 = acc[vb][4 * i4 + 1] * rn * gn[1] * sigmoidf_(bfhi(ow.x));
;             const float y2 = acc[vb][4 * i4 + 2] * rn * gn[2] * sigmoidf_(bflo(ow.y)), y3 = acc[vb][4 * i4 + 3] * rn * gn[3] * sigmoidf_(bfhi(ow.y));
;             u32x2 w; w.x = pk2(y0, y1); w.y = pk2(y2, y3); if (st) *(u32x2*)(orow + v0) = w; if (i4 == 3) asm volatile("" ::: "memory"); }
	v_pk_mul_f32 v[0:1], v[48:49], v[0:1]
	v_pk_mul_f32 v[2:3], v[50:51], v[2:3]
	v_pk_mul_f32 v[0:1], v[108:109], v[0:1]
	v_pk_mul_f32 v[2:3], v[110:111], v[2:3]
	v_cvt_pk_bf16_f32 v0, v0, v1
	v_cvt_pk_bf16_f32 v1, v2, v3
	global_store_dwordx2 v[70:71], v[0:1], off offset:32
	v_pk_mul_f32 v[0:1], v[130:131], v[4:5] op_sel_hi:[1,0]
	v_pk_mul_f32 v[2:3], v[126:127], v[4:5] op_sel_hi:[1,0]
	s_waitcnt lgkmcnt(0)
	v_pk_mul_f32 v[0:1], v[52:53], v[0:1]
	v_pk_mul_f32 v[2:3], v[54:55], v[2:3]
	v_pk_mul_f32 v[0:1], v[120:121], v[0:1]
	v_pk_mul_f32 v[2:3], v[122:123], v[2:3]
	v_cvt_pk_bf16_f32 v0, v0, v1
	v_cvt_pk_bf16_f32 v1, v2, v3
	global_store_dwordx2 v[70:71], v[0:1], off offset:48
	s_waitcnt vmcnt(4)
	v_mov_b32_e32 v12, v168
	v_mov_b32_e32 v13, v169
	ds_read_b128 v[0:3], v81 offset:20608
	ds_read_b128 v[8:11], v81 offset:20640
	v_lshlrev_b32_e32 v5, 16, v12
	v_mul_f32_e32 v5, 0xbfb8aa3b, v5
	v_exp_f32_e32 v5, v5
	s_nop 0
	v_add_f32_e32 v5, 1.0, v5
	v_rcp_f32_e32 v28, v5
	v_pk_mul_f32 v[30:31], v[138:139], v[4:5] op_sel_hi:[1,0]
	v_and_b32_e32 v5, 0xffff0000, v12
	v_mul_f32_e32 v5, 0xbfb8aa3b, v5
	v_exp_f32_e32 v5, v5
	s_waitcnt lgkmcnt(1)
	v_pk_mul_f32 v[0:1], v[0:1], v[30:31]
	v_add_f32_e32 v5, 1.0, v5
	v_rcp_f32_e32 v29, v5
	v_lshlrev_b32_e32 v5, 16, v13
	v_mul_f32_e32 v5, 0xbfb8aa3b, v5
	v_exp_f32_e32 v5, v5
	v_pk_mul_f32 v[0:1], v[28:29], v[0:1]
	v_add_f32_e32 v5, 1.0, v5
	v_rcp_f32_e32 v12, v5
	v_pk_mul_f32 v[28:29], v[134:135], v[4:5] op_sel_hi:[1,0]
	v_and_b32_e32 v5, 0xffff0000, v13
	v_mul_f32_e32 v5, 0xbfb8aa3b, v5
	v_exp_f32_e32 v5, v5
	v_pk_mul_f32 v[2:3], v[2:3], v[28:29]
	v_cvt_pk_bf16_f32 v0, v0, v1
	v_add_f32_e32 v5, 1.0, v5
	v_rcp_f32_e32 v13, v5
	s_nop 0
	v_pk_mul_f32 v[2:3], v[12:13], v[2:3]
	s_nop 0
	v_cvt_pk_bf16_f32 v1, v2, v3
	global_store_dwordx2 v[70:71], v[0:1], off offset:64
	v_mov_b32_e32 v0, v170
	v_mov_b32_e32 v1, v171
	v_pk_mul_f32 v[12:13], v[118:119], v[4:5] op_sel_hi:[1,0]
	v_lshlrev_b32_e32 v2, 16, v0
	v_and_b32_e32 v0, 0xffff0000, v0
	v_mul_f32_e32 v0, 0xbfb8aa3b, v0
	v_exp_f32_e32 v0, v0
	v_mul_f32_e32 v2, 0xbfb8aa3b, v2
	v_exp_f32_e32 v2, v2
	s_waitcnt lgkmcnt(0)
	v_pk_mul_f32 v[8:9], v[8:9], v[12:13]
	v_add_f32_e32 v0, 1.0, v0
	v_rcp_f32_e32 v3, v0
	v_lshlrev_b32_e32 v0, 16, v1
	v_and_b32_e32 v1, 0xffff0000, v1
	v_mul_f32_e32 v0, 0xbfb8aa3b, v0
	v_mul_f32_e32 v1, 0xbfb8aa3b, v1
	v_exp_f32_e32 v0, v0
	v_exp_f32_e32 v1, v1
	v_add_f32_e32 v2, 1.0, v2
	v_rcp_f32_e32 v2, v2
	v_add_f32_e32 v0, 1.0, v0
	v_add_f32_e32 v1, 1.0, v1
	v_rcp_f32_e32 v0, v0
	v_rcp_f32_e32 v1, v1
	v_pk_mul_f32 v[2:3], v[2:3], v[8:9]
	v_pk_mul_f32 v[8:9], v[116:117], v[4:5] op_sel_hi:[1,0]
	v_cvt_pk_bf16_f32 v2, v2, v3
	v_pk_mul_f32 v[8:9], v[10:11], v[8:9]
	s_nop 0
	v_pk_mul_f32 v[0:1], v[0:1], v[8:9]
	v_mov_b32_e32 v8, v172
	v_mov_b32_e32 v9, v173
	v_cvt_pk_bf16_f32 v3, v0, v1
	global_store_dwordx2 v[70:71], v[2:3], off offset:80
	ds_read_b128 v[0:3], v81 offset:20672
	v_lshlrev_b32_e32 v5, 16, v8
	v_mul_f32_e32 v5, 0xbfb8aa3b, v5
	v_exp_f32_e32 v5, v5
	s_nop 0
	v_add_f32_e32 v5, 1.0, v5
	v_rcp_f32_e32 v10, v5
	v_pk_mul_f32 v[12:13], v[62:63], v[4:5] op_sel_hi:[1,0]
	v_and_b32_e32 v5, 0xffff0000, v8
	v_mul_f32_e32 v5, 0xbfb8aa3b, v5
	v_exp_f32_e32 v5, v5
	s_waitcnt lgkmcnt(0)
	v_pk_mul_f32 v[0:1], v[0:1], v[12:13]
	v_add_f32_e32 v5, 1.0, v5
	v_rcp_f32_e32 v11, v5
	v_lshlrev_b32_e32 v5, 16, v9
	v_mul_f32_e32 v5, 0xbfb8aa3b, v5
	v_exp_f32_e32 v5, v5
	v_pk_mul_f32 v[0:1], v[10:11], v[0:1]
	v_add_f32_e32 v5, 1.0, v5
	v_rcp_f32_e32 v8, v5
	v_pk_mul_f32 v[10:11], v[60:61], v[4:5] op_sel_hi:[1,0]
	v_and_b32_e32 v5, 0xffff0000, v9
	v_mul_f32_e32 v5, 0xbfb8aa3b, v5
	v_exp_f32_e32 v5, v5
	v_pk_mul_f32 v[2:3], v[2:3], v[10:11]
	v_cvt_pk_bf16_f32 v0, v0, v1
	v_add_f32_e32 v5, 1.0, v5
	v_rcp_f32_e32 v9, v5
	s_nop 0
	v_pk_mul_f32 v[2:3], v[8:9], v[2:3]
	v_mov_b32_e32 v8, v174
	v_mov_b32_e32 v9, v175
	v_cvt_pk_bf16_f32 v1, v2, v3
	global_store_dwordx2 v[70:71], v[0:1], off offset:96
	ds_read_b128 v[0:3], v81 offset:20704
	v_lshlrev_b32_e32 v5, 16, v8
	v_mul_f32_e32 v5, 0xbfb8aa3b, v5
	v_exp_f32_e32 v5, v5
	s_nop 0
	v_add_f32_e32 v5, 1.0, v5
	v_rcp_f32_e32 v10, v5
	v_pk_mul_f32 v[12:13], v[44:45], v[4:5] op_sel_hi:[1,0]
	v_and_b32_e32 v5, 0xffff0000, v8
	v_mul_f32_e32 v5, 0xbfb8aa3b, v5
	v_exp_f32_e32 v5, v5
	s_waitcnt lgkmcnt(0)
	v_pk_mul_f32 v[0:1], v[0:1], v[12:13]
	v_add_f32_e32 v5, 1.0, v5
	v_rcp_f32_e32 v11, v5
	v_lshlrev_b32_e32 v5, 16, v9
	v_mul_f32_e32 v5, 0xbfb8aa3b, v5
	v_exp_f32_e32 v5, v5
	v_pk_mul_f32 v[0:1], v[10:11], v[0:1]
	v_add_f32_e32 v5, 1.0, v5
	v_rcp_f32_e32 v8, v5
	v_pk_mul_f32 v[10:11], v[46:47], v[4:5] op_sel_hi:[1,0]
	v_and_b32_e32 v5, 0xffff0000, v9
	v_mul_f32_e32 v5, 0xbfb8aa3b, v5
	v_exp_f32_e32 v5, v5
	v_pk_mul_f32 v[2:3], v[2:3], v[10:11]
	v_cvt_pk_bf16_f32 v0, v0, v1
	v_add_f32_e32 v5, 1.0, v5
	v_rcp_f32_e32 v9, v5
	s_nop 0
	v_pk_mul_f32 v[2:3], v[8:9], v[2:3]
	s_nop 0
	v_cvt_pk_bf16_f32 v1, v2, v3
	global_store_dwordx2 v[70:71], v[0:1], off offset:112
	v_mov_b32_e32 v12, v176
	v_mov_b32_e32 v13, v177
	ds_read_b128 v[0:3], v81 offset:20736
	ds_read_b128 v[8:11], v81 offset:20768
	v_lshlrev_b32_e32 v5, 16, v12
	v_mul_f32_e32 v5, 0xbfb8aa3b, v5
	v_exp_f32_e32 v5, v5
	s_nop 0
	v_add_f32_e32 v5, 1.0, v5
	v_rcp_f32_e32 v28, v5
	v_pk_mul_f32 v[30:31], v[42:43], v[4:5] op_sel_hi:[1,0]
	v_and_b32_e32 v5, 0xffff0000, v12
	v_mul_f32_e32 v5, 0xbfb8aa3b, v5
	v_exp_f32_e32 v5, v5
	s_waitcnt lgkmcnt(1)
; #define LAS __attribute__((address_space(3)))
; __device__ __forceinline__ unsigned pk2(float lo, float hi) { f32x2_t v = {lo, hi}; bf16x2_t b = __builtin_convertvector(v, bf16x2_t); return __builtin_bit_cast(unsigned, b); }
; __device__ __forceinline__ float bflo(unsigned w) { return __uint_as_float(w << 16); }
; __device__ __forceinline__ float bfhi(unsigned w) { return __uint_as_float(w & 0xffff0000u); }
; __device__ __forceinline__ float sigmoidf_(float x) { return __builtin_amdgcn_rcpf(1.f + fexp(-x)); }
; template <bool SAMPLE>
; __device__ __forceinline__ void mout_task(Ctx& C, int l, int unit, int h, int tb, const LAS float* cwl, const LAS float* gainl, LAS float* gsbuf, LAS s16x8* qfl, const bool st) {
;     ...
;         for (int i4 = 0; i4 < 4; ++i4) { const int v0 = 32 * vb + 8 * i4 + 4 * hi2;
;             const u32x2 ow = *(const u32x2*)(orow + v0); const f32x4 gn = *(const LAS f32x4*)(gainl + h * 128 + v0);
;             const float y0 = acc[vb][4 * i4] * rn * gn[0] * sigmoidf_(bflo(ow.x)), y1 = acc[vb][4 * i4 + 1] * rn * gn[1] * sigmoidf_(bfhi(ow.x));
;             const float y2 = acc[vb][4 * i4 + 2] * rn * gn[2] * sigmoidf_(bflo(ow.y)), y3 = acc[vb][4 * i4 + 3] * rn * gn[3] * sigmoidf_(bfhi(ow.y));
;             u32x2 w; w.x = pk2(y0, y1); w.y = pk2(y2, y3); if (st) *(u32x2*)(orow + v0) = w; if (i4 == 3) asm volatile("" ::: "memory"); }
	v_pk_mul_f32 v[0:1], v[0:1], v[30:31]
	v_add_f32_e32 v5, 1.0, v5
	v_rcp_f32_e32 v29, v5
	v_lshlrev_b32_e32 v5, 16, v13
	v_mul_f32_e32 v5, 0xbfb8aa3b, v5
	v_exp_f32_e32 v5, v5
	v_pk_mul_f32 v[0:1], v[28:29], v[0:1]
	v_add_f32_e32 v5, 1.0, v5
	v_rcp_f32_e32 v12, v5
	v_pk_mul_f32 v[28:29], v[40:41], v[4:5] op_sel_hi:[1,0]
	v_and_b32_e32 v5, 0xffff0000, v13
	v_mul_f32_e32 v5, 0xbfb8aa3b, v5
	v_exp_f32_e32 v5, v5
	v_pk_mul_f32 v[2:3], v[2:3], v[28:29]
	v_cvt_pk_bf16_f32 v0, v0, v1
	v_add_f32_e32 v5, 1.0, v5
	v_rcp_f32_e32 v13, v5
	s_nop 0
	v_pk_mul_f32 v[2:3], v[12:13], v[2:3]
	s_nop 0
	v_cvt_pk_bf16_f32 v1, v2, v3
	global_store_dwordx2 v[70:71], v[0:1], off offset:128
	v_mov_b32_e32 v0, v180
	v_mov_b32_e32 v1, v181
	v_pk_mul_f32 v[12:13], v[38:39], v[4:5] op_sel_hi:[1,0]
	v_lshlrev_b32_e32 v2, 16, v0
	v_and_b32_e32 v0, 0xffff0000, v0
	v_mul_f32_e32 v0, 0xbfb8aa3b, v0
	v_exp_f32_e32 v0, v0
	v_mul_f32_e32 v2, 0xbfb8aa3b, v2
	v_exp_f32_e32 v2, v2
	s_waitcnt lgkmcnt(0)
	v_pk_mul_f32 v[8:9], v[8:9], v[12:13]
	v_add_f32_e32 v0, 1.0, v0
	v_rcp_f32_e32 v3, v0
	v_lshlrev_b32_e32 v0, 16, v1
	v_and_b32_e32 v1, 0xffff0000, v1
	v_mul_f32_e32 v0, 0xbfb8aa3b, v0
	v_mul_f32_e32 v1, 0xbfb8aa3b, v1
	v_exp_f32_e32 v0, v0
	v_exp_f32_e32 v1, v1
	v_add_f32_e32 v2, 1.0, v2
	v_rcp_f32_e32 v2, v2
	v_add_f32_e32 v0, 1.0, v0
	v_add_f32_e32 v1, 1.0, v1
	v_rcp_f32_e32 v0, v0
	v_rcp_f32_e32 v1, v1
	v_pk_mul_f32 v[2:3], v[2:3], v[8:9]
	v_pk_mul_f32 v[8:9], v[36:37], v[4:5] op_sel_hi:[1,0]
	v_cvt_pk_bf16_f32 v2, v2, v3
	v_pk_mul_f32 v[8:9], v[10:11], v[8:9]
	s_nop 0
	v_pk_mul_f32 v[0:1], v[0:1], v[8:9]
	v_mov_b32_e32 v8, v182
	v_mov_b32_e32 v9, v183
	v_cvt_pk_bf16_f32 v3, v0, v1
	global_store_dwordx2 v[70:71], v[2:3], off offset:144
	ds_read_b128 v[0:3], v81 offset:20800
	v_lshlrev_b32_e32 v5, 16, v8
	v_mul_f32_e32 v5, 0xbfb8aa3b, v5
	v_exp_f32_e32 v5, v5
	s_nop 0
	v_add_f32_e32 v5, 1.0, v5
	v_rcp_f32_e32 v10, v5
	v_pk_mul_f32 v[12:13], v[34:35], v[4:5] op_sel_hi:[1,0]
	v_and_b32_e32 v5, 0xffff0000, v8
	v_mul_f32_e32 v5, 0xbfb8aa3b, v5
	v_exp_f32_e32 v5, v5
	s_waitcnt lgkmcnt(0)
	v_pk_mul_f32 v[0:1], v[0:1], v[12:13]
	v_add_f32_e32 v5, 1.0, v5
	v_rcp_f32_e32 v11, v5
	v_lshlrev_b32_e32 v5, 16, v9
	v_mul_f32_e32 v5, 0xbfb8aa3b, v5
	v_exp_f32_e32 v5, v5
	v_pk_mul_f32 v[0:1], v[10:11], v[0:1]
	v_add_f32_e32 v5, 1.0, v5
	v_rcp_f32_e32 v8, v5
	v_pk_mul_f32 v[10:11], v[32:33], v[4:5] op_sel_hi:[1,0]
	v_and_b32_e32 v5, 0xffff0000, v9
	v_mul_f32_e32 v5, 0xbfb8aa3b, v5
	v_exp_f32_e32 v5, v5
	v_pk_mul_f32 v[2:3], v[2:3], v[10:11]
	v_cvt_pk_bf16_f32 v0, v0, v1
	v_add_f32_e32 v5, 1.0, v5
	v_rcp_f32_e32 v9, v5
	s_nop 0
	v_pk_mul_f32 v[2:3], v[8:9], v[2:3]
	v_mov_b32_e32 v8, v186
	v_mov_b32_e32 v9, v187
	v_cvt_pk_bf16_f32 v1, v2, v3
	global_store_dwordx2 v[70:71], v[0:1], off offset:160
	ds_read_b128 v[0:3], v81 offset:20832
	v_lshlrev_b32_e32 v5, 16, v8
	v_mul_f32_e32 v5, 0xbfb8aa3b, v5
	v_exp_f32_e32 v5, v5
	s_nop 0
	v_add_f32_e32 v5, 1.0, v5
	v_rcp_f32_e32 v10, v5
	v_pk_mul_f32 v[12:13], v[26:27], v[4:5] op_sel_hi:[1,0]
	v_and_b32_e32 v5, 0xffff0000, v8
	v_mul_f32_e32 v5, 0xbfb8aa3b, v5
	v_exp_f32_e32 v5, v5
	s_waitcnt lgkmcnt(0)
	v_pk_mul_f32 v[0:1], v[0:1], v[12:13]
	v_add_f32_e32 v5, 1.0, v5
	v_rcp_f32_e32 v11, v5
	v_lshlrev_b32_e32 v5, 16, v9
	v_mul_f32_e32 v5, 0xbfb8aa3b, v5
	v_exp_f32_e32 v5, v5
	v_pk_mul_f32 v[0:1], v[10:11], v[0:1]
	v_add_f32_e32 v5, 1.0, v5
	v_rcp_f32_e32 v8, v5
	v_pk_mul_f32 v[10:11], v[24:25], v[4:5] op_sel_hi:[1,0]
	v_and_b32_e32 v5, 0xffff0000, v9
	v_mul_f32_e32 v5, 0xbfb8aa3b, v5
	v_exp_f32_e32 v5, v5
	v_pk_mul_f32 v[2:3], v[2:3], v[10:11]
	v_cvt_pk_bf16_f32 v0, v0, v1
	v_add_f32_e32 v5, 1.0, v5
	v_rcp_f32_e32 v9, v5
	s_nop 0
	v_pk_mul_f32 v[2:3], v[8:9], v[2:3]
	s_nop 0
	v_cvt_pk_bf16_f32 v1, v2, v3
	global_store_dwordx2 v[70:71], v[0:1], off offset:176
	v_mov_b32_e32 v12, v194
	v_mov_b32_e32 v13, v195
	ds_read_b128 v[0:3], v81 offset:20864
	ds_read_b128 v[8:11], v81 offset:20896
	v_lshlrev_b32_e32 v5, 16, v12
	v_mul_f32_e32 v5, 0xbfb8aa3b, v5
	v_exp_f32_e32 v5, v5
	s_nop 0
	v_add_f32_e32 v5, 1.0, v5
	v_rcp_f32_e32 v24, v5
	v_pk_mul_f32 v[22:23], v[22:23], v[4:5] op_sel_hi:[1,0]
	v_and_b32_e32 v5, 0xffff0000, v12
	v_mul_f32_e32 v5, 0xbfb8aa3b, v5
	v_exp_f32_e32 v5, v5
	s_waitcnt lgkmcnt(1)
; #define LAS __attribute__((address_space(3)))
; __device__ __forceinline__ unsigned pk2(float lo, float hi) { f32x2_t v = {lo, hi}; bf16x2_t b = __builtin_convertvector(v, bf16x2_t); return __builtin_bit_cast(unsigned, b); }
; __device__ __forceinline__ float bflo(unsigned w) { return __uint_as_float(w << 16); }
; __device__ __forceinline__ float bfhi(unsigned w) { return __uint_as_float(w & 0xffff0000u); }
; __device__ __forceinline__ float sigmoidf_(float x) { return __builtin_amdgcn_rcpf(1.f + fexp(-x)); }
; #define LDS_WAIT() asm volatile("s_waitcnt lgkmcnt(0)" ::: "memory")
; template <bool SAMPLE>
; __device__ __forceinline__ void mout_task(Ctx& C, int l, int unit, int h, int tb, const LAS float* cwl, const LAS float* gainl, LAS float* gsbuf, LAS s16x8* qfl, const bool st) {
;     ...
;         for (int i4 = 0; i4 < 4; ++i4) { const int v0 = 32 * vb + 8 * i4 + 4 * hi2;
;             const u32x2 ow = *(const u32x2*)(orow + v0); const f32x4 gn = *(const LAS f32x4*)(gainl + h * 128 + v0);
;             const float y0 = acc[vb][4 * i4] * rn * gn[0] * sigmoidf_(bflo(ow.x)), y1 = acc[vb][4 * i4 + 1] * rn * gn[1] * sigmoidf_(bfhi(ow.x));
;             const float y2 = acc[vb][4 * i4 + 2] * rn * gn[2] * sigmoidf_(bflo(ow.y)), y3 = acc[vb][4 * i4 + 3] * rn * gn[3] * sigmoidf_(bfhi(ow.y));
;             u32x2 w; w.x = pk2(y0, y1); w.y = pk2(y2, y3); if (st) *(u32x2*)(orow + v0) = w; if (i4 == 3) asm volatile("" ::: "memory"); }
;     LDS_WAIT();
	v_pk_mul_f32 v[0:1], v[0:1], v[22:23]
	v_add_f32_e32 v5, 1.0, v5
	v_rcp_f32_e32 v25, v5
	v_lshlrev_b32_e32 v5, 16, v13
	v_mul_f32_e32 v5, 0xbfb8aa3b, v5
	v_exp_f32_e32 v5, v5
	v_pk_mul_f32 v[0:1], v[24:25], v[0:1]
	v_add_f32_e32 v5, 1.0, v5
	v_rcp_f32_e32 v12, v5
	v_pk_mul_f32 v[20:21], v[20:21], v[4:5] op_sel_hi:[1,0]
	v_and_b32_e32 v5, 0xffff0000, v13
	v_mul_f32_e32 v5, 0xbfb8aa3b, v5
	v_exp_f32_e32 v5, v5
	v_pk_mul_f32 v[2:3], v[2:3], v[20:21]
	v_cvt_pk_bf16_f32 v0, v0, v1
	v_add_f32_e32 v5, 1.0, v5
	v_rcp_f32_e32 v13, v5
	s_nop 0
	v_pk_mul_f32 v[2:3], v[12:13], v[2:3]
	s_nop 0
	v_cvt_pk_bf16_f32 v1, v2, v3
	global_store_dwordx2 v[70:71], v[0:1], off offset:192
	v_mov_b32_e32 v0, v196
	v_mov_b32_e32 v1, v197
	v_pk_mul_f32 v[12:13], v[18:19], v[4:5] op_sel_hi:[1,0]
	v_lshlrev_b32_e32 v2, 16, v0
	v_and_b32_e32 v0, 0xffff0000, v0
	v_mul_f32_e32 v0, 0xbfb8aa3b, v0
	v_exp_f32_e32 v0, v0
	v_mul_f32_e32 v2, 0xbfb8aa3b, v2
	v_exp_f32_e32 v2, v2
	s_waitcnt lgkmcnt(0)
	v_pk_mul_f32 v[8:9], v[8:9], v[12:13]
	v_add_f32_e32 v0, 1.0, v0
	v_rcp_f32_e32 v3, v0
	v_lshlrev_b32_e32 v0, 16, v1
	v_and_b32_e32 v1, 0xffff0000, v1
	v_mul_f32_e32 v0, 0xbfb8aa3b, v0
	v_mul_f32_e32 v1, 0xbfb8aa3b, v1
	v_exp_f32_e32 v0, v0
	v_exp_f32_e32 v1, v1
	v_add_f32_e32 v2, 1.0, v2
	v_rcp_f32_e32 v2, v2
	v_add_f32_e32 v0, 1.0, v0
	v_add_f32_e32 v1, 1.0, v1
	v_rcp_f32_e32 v0, v0
	v_rcp_f32_e32 v1, v1
	v_pk_mul_f32 v[2:3], v[2:3], v[8:9]
	v_pk_mul_f32 v[8:9], v[16:17], v[4:5] op_sel_hi:[1,0]
	v_cvt_pk_bf16_f32 v2, v2, v3
	v_pk_mul_f32 v[8:9], v[10:11], v[8:9]
	s_nop 0
	v_pk_mul_f32 v[0:1], v[0:1], v[8:9]
	v_mov_b32_e32 v8, v198
	v_mov_b32_e32 v9, v199
	v_cvt_pk_bf16_f32 v3, v0, v1
	global_store_dwordx2 v[70:71], v[2:3], off offset:208
	ds_read_b128 v[0:3], v81 offset:20928
	v_lshlrev_b32_e32 v5, 16, v8
	v_mul_f32_e32 v5, 0xbfb8aa3b, v5
	v_exp_f32_e32 v5, v5
	s_nop 0
	v_add_f32_e32 v5, 1.0, v5
	v_rcp_f32_e32 v10, v5
	v_pk_mul_f32 v[6:7], v[6:7], v[4:5] op_sel_hi:[1,0]
	v_and_b32_e32 v5, 0xffff0000, v8
	v_mul_f32_e32 v5, 0xbfb8aa3b, v5
	v_exp_f32_e32 v5, v5
	s_waitcnt lgkmcnt(0)
	v_pk_mul_f32 v[0:1], v[0:1], v[6:7]
	v_add_f32_e32 v5, 1.0, v5
	v_rcp_f32_e32 v11, v5
	v_lshlrev_b32_e32 v5, 16, v9
	v_mul_f32_e32 v5, 0xbfb8aa3b, v5
	v_exp_f32_e32 v5, v5
	v_pk_mul_f32 v[0:1], v[10:11], v[0:1]
	v_add_f32_e32 v5, 1.0, v5
	v_rcp_f32_e32 v6, v5
	v_and_b32_e32 v5, 0xffff0000, v9
	v_mul_f32_e32 v5, 0xbfb8aa3b, v5
	v_exp_f32_e32 v5, v5
	v_cvt_pk_bf16_f32 v0, v0, v1
	v_add_f32_e32 v5, 1.0, v5
	v_rcp_f32_e32 v7, v5
	v_pk_mul_f32 v[8:9], v[72:73], v[4:5] op_sel_hi:[1,0]
	s_nop 0
	v_pk_mul_f32 v[2:3], v[2:3], v[8:9]
	s_nop 0
	v_pk_mul_f32 v[2:3], v[6:7], v[2:3]
	v_mov_b32_e32 v6, v214
	v_mov_b32_e32 v7, v215
	v_cvt_pk_bf16_f32 v1, v2, v3
	global_store_dwordx2 v[70:71], v[0:1], off offset:224
	ds_read_b128 v[0:3], v81 offset:20960
	v_lshlrev_b32_e32 v5, 16, v6
	v_mul_f32_e32 v5, 0xbfb8aa3b, v5
	v_exp_f32_e32 v5, v5
	s_nop 0
	v_add_f32_e32 v5, 1.0, v5
	v_rcp_f32_e32 v8, v5
	v_and_b32_e32 v5, 0xffff0000, v6
	v_mul_f32_e32 v5, 0xbfb8aa3b, v5
	v_exp_f32_e32 v5, v5
	s_nop 0
	v_add_f32_e32 v5, 1.0, v5
	v_rcp_f32_e32 v9, v5
	v_pk_mul_f32 v[10:11], v[68:69], v[4:5] op_sel_hi:[1,0]
	v_lshlrev_b32_e32 v5, 16, v7
	v_mul_f32_e32 v5, 0xbfb8aa3b, v5
	v_exp_f32_e32 v5, v5
	s_waitcnt lgkmcnt(0)
	v_pk_mul_f32 v[0:1], v[0:1], v[10:11]
	v_add_f32_e32 v5, 1.0, v5
	v_rcp_f32_e32 v6, v5
	v_and_b32_e32 v5, 0xffff0000, v7
	v_mul_f32_e32 v5, 0xbfb8aa3b, v5
	v_exp_f32_e32 v5, v5
	v_pk_mul_f32 v[0:1], v[8:9], v[0:1]
	v_add_f32_e32 v5, 1.0, v5
	v_rcp_f32_e32 v7, v5
	v_pk_mul_f32 v[4:5], v[14:15], v[4:5] op_sel_hi:[1,0]
	v_cvt_pk_bf16_f32 v0, v0, v1
	v_pk_mul_f32 v[2:3], v[2:3], v[4:5]
	s_nop 0
	v_pk_mul_f32 v[2:3], v[6:7], v[2:3]
	s_nop 0
	v_cvt_pk_bf16_f32 v1, v2, v3
	global_store_dwordx2 v[70:71], v[0:1], off offset:240
	s_waitcnt lgkmcnt(0)
	s_branch .LBB0_903
